# K-loop load segments: m0 temporaries folded into the m0 writes, buffer-1 constants as literals, LDS read bases in spare VGPRs (6 SALU + 2 VALU fewer per iteration)
# speedup vs baseline: 1.0049x; 1.0049x over previous
; #define PG8_STAGE(bufoff, gbase, voff) do { _Pragma("unroll") for (int _i = 0; _i < 2; ++_i) \
;         __builtin_amdgcn_global_load_lds((const unsigned*)((const char*)(gbase) + (voff)[_i]), (PG8_LAS unsigned*)(lds + (bufoff) + ldsw + _i * 8192), 16, 0, 0); } while (0)
; #define PG8_LDA(dst, b, h) do { _Pragma("unroll") for (int m = 0; m < 4; ++m) _Pragma("unroll") for (int k = 0; k < 2; ++k) dst[m][k] = *(const PG8_LAS bf16x8*)(lds + PG8_SA(b, h) + aoff + m * 2048 + k * 1024); } while (0)
; #define PG8_LDB(dst, b, h) do { _Pragma("unroll") for (int n = 0; n < 2; ++n) _Pragma("unroll") for (int k = 0; k < 2; ++k) dst[n][k] = *(const PG8_LAS bf16x8*)(lds + PG8_SB(b, h) + boff + n * 2048 + k * 1024); } while (0)
; #define PG8_MMA(ai, bj, At, Bt) do { __builtin_amdgcn_s_setprio(1); _Pragma("unroll") for (int m = 0; m < 4; ++m) _Pragma("unroll") for (int n = 0; n < 2; ++n) _Pragma("unroll") for (int k = 0; k < 2; ++k) \
;         acc[ai][bj][m][n] = __builtin_amdgcn_mfma_f32_16x16x32_bf16(Bt[n][k], At[m][k], acc[ai][bj][m][n], 0, 0, 0); __builtin_amdgcn_s_setprio(0); } while (0)
; #define PG8_WAIT_V(n) asm volatile("s_waitcnt vmcnt(" #n ")" ::: "memory")
; #define PG8_WAIT_L(n) asm volatile("s_waitcnt lgkmcnt(" #n ")" ::: "memory")
; #define PG8_BAR __builtin_amdgcn_s_barrier()
; #define PG8_SCHED __builtin_amdgcn_sched_barrier(0)
; template <class Epi, class Sched, bool ALIGN_EPI = false, bool SP2 = false, bool KSEG = false>
; __device__ __forceinline__ void gemm_phase(PG8_LAS unsigned char* lds, const Gemm g, const Sched& S, const Epi& E) {
;     ...
;             PG8_LDB(B0, 0, 0); PG8_LDB(B1, 0, 1); PG8_SCHED; PG8_LDA(At, 0, 0); PG8_STAGE(PG8_SA(1, 1), a1 + hstep, voffA);
;             PG8_WAIT_V(8); PG8_WAIT_L(0); PG8_BAR; PG8_MMA(0, 0, At, B0); PG8_MMA(0, 1, At, B1); PG8_BAR; PG8_SCHED;
;             PG8_LDA(At, 0, 1); PG8_STAGE(PG8_SB(0, 0), b2, voffB); PG8_STAGE(PG8_SB(0, 1), b2 + hstep, voffB); PG8_STAGE(PG8_SA(0, 0), a2, voffA);
;             PG8_WAIT_V(8); PG8_WAIT_L(0); PG8_BAR; PG8_MMA(1, 0, At, B0); PG8_MMA(1, 1, At, B1); PG8_BAR; PG8_SCHED;
.LBB0_120:
	ds_read_b128 v[146:149], v156
	ds_read_b128 v[150:153], v156 offset:1024
	ds_read_b128 v[160:163], v156 offset:2048
	ds_read_b128 v[164:167], v156 offset:3072
	ds_read_b128 v[168:171], v157
	ds_read_b128 v[172:175], v157 offset:1024
	ds_read_b128 v[176:179], v157 offset:2048
	ds_read_b128 v[180:183], v157 offset:3072
	s_mov_b32 m0, s51
	v_lshl_add_u64 v[216:217], s[98:99], 0, v[136:137]
	global_load_lds_dwordx4 v[216:217], off
	s_mov_b32 m0, s58
	v_lshl_add_u64 v[216:217], s[98:99], 0, v[132:133]
	global_load_lds_dwordx4 v[216:217], off
	v_lshl_add_u64 v[216:217], s[28:29], 0, v[138:139]
	s_add_i32 m0, s27, 0xc000
	ds_read_b128 v[184:187], v158
	ds_read_b128 v[188:191], v158 offset:1024
	ds_read_b128 v[192:195], v158 offset:2048
	ds_read_b128 v[196:199], v158 offset:3072
	ds_read_b128 v[200:203], v158 offset:4096
	ds_read_b128 v[204:207], v158 offset:5120
	ds_read_b128 v[208:211], v158 offset:6144
	ds_read_b128 v[212:215], v158 offset:7168
	global_load_lds_dwordx4 v[216:217], off
	s_add_i32 m0, s27, 0xe000
	v_lshl_add_u64 v[216:217], s[28:29], 0, v[140:141]
	global_load_lds_dwordx4 v[216:217], off
	s_waitcnt vmcnt(8) lgkmcnt(0)
	s_barrier
	s_setprio 1
	v_mfma_f32_16x16x32_bf16 v[126:129], v[146:149], v[184:187], v[126:129]
	v_mfma_f32_16x16x32_bf16 v[122:125], v[160:163], v[184:187], v[122:125]
	v_mfma_f32_16x16x32_bf16 v[110:113], v[146:149], v[192:195], v[110:113]
	v_mfma_f32_16x16x32_bf16 v[106:109], v[160:163], v[192:195], v[106:109]
	v_mfma_f32_16x16x32_bf16 v[94:97], v[146:149], v[200:203], v[94:97]
	v_mfma_f32_16x16x32_bf16 v[90:93], v[160:163], v[200:203], v[90:93]
	v_mfma_f32_16x16x32_bf16 v[78:81], v[146:149], v[208:211], v[78:81]
	v_mfma_f32_16x16x32_bf16 v[74:77], v[160:163], v[208:211], v[74:77]
	v_mfma_f32_16x16x32_bf16 v[126:129], v[150:153], v[188:191], v[126:129]
	v_mfma_f32_16x16x32_bf16 v[122:125], v[164:167], v[188:191], v[122:125]
	v_mfma_f32_16x16x32_bf16 v[110:113], v[150:153], v[196:199], v[110:113]
	v_mfma_f32_16x16x32_bf16 v[106:109], v[164:167], v[196:199], v[106:109]
	v_mfma_f32_16x16x32_bf16 v[94:97], v[150:153], v[204:207], v[94:97]
	v_mfma_f32_16x16x32_bf16 v[90:93], v[164:167], v[204:207], v[90:93]
	v_mfma_f32_16x16x32_bf16 v[78:81], v[150:153], v[212:215], v[78:81]
	v_mfma_f32_16x16x32_bf16 v[74:77], v[164:167], v[212:215], v[74:77]
	s_setprio 0
	s_setprio 1
	v_mfma_f32_16x16x32_bf16 v[118:121], v[168:171], v[184:187], v[118:121]
	v_mfma_f32_16x16x32_bf16 v[114:117], v[176:179], v[184:187], v[114:117]
	v_mfma_f32_16x16x32_bf16 v[102:105], v[168:171], v[192:195], v[102:105]
	v_mfma_f32_16x16x32_bf16 v[98:101], v[176:179], v[192:195], v[98:101]
	v_mfma_f32_16x16x32_bf16 v[86:89], v[168:171], v[200:203], v[86:89]
	v_mfma_f32_16x16x32_bf16 v[82:85], v[176:179], v[200:203], v[82:85]
	v_mfma_f32_16x16x32_bf16 v[70:73], v[168:171], v[208:211], v[70:73]
	v_mfma_f32_16x16x32_bf16 v[66:69], v[176:179], v[208:211], v[66:69]
	v_mfma_f32_16x16x32_bf16 v[118:121], v[172:175], v[188:191], v[118:121]
	v_mfma_f32_16x16x32_bf16 v[114:117], v[180:183], v[188:191], v[114:117]
	v_mfma_f32_16x16x32_bf16 v[102:105], v[172:175], v[196:199], v[102:105]
	v_mfma_f32_16x16x32_bf16 v[98:101], v[180:183], v[196:199], v[98:101]
	v_mfma_f32_16x16x32_bf16 v[86:89], v[172:175], v[204:207], v[86:89]
	v_mfma_f32_16x16x32_bf16 v[82:85], v[180:183], v[204:207], v[82:85]
	v_mfma_f32_16x16x32_bf16 v[70:73], v[172:175], v[212:215], v[70:73]
	v_mfma_f32_16x16x32_bf16 v[66:69], v[180:183], v[212:215], v[66:69]
	s_setprio 0
	s_barrier
	v_lshl_add_u64 v[216:217], s[30:31], 0, v[134:135]
	s_add_i32 m0, s60, s44
	ds_read_b128 v[184:187], v158 offset:16384
	ds_read_b128 v[188:191], v158 offset:17408
	ds_read_b128 v[192:195], v158 offset:18432
	ds_read_b128 v[196:199], v158 offset:19456
	ds_read_b128 v[200:203], v158 offset:20480
	ds_read_b128 v[204:207], v158 offset:21504
	ds_read_b128 v[208:211], v158 offset:22528
	ds_read_b128 v[212:215], v158 offset:23552
	global_load_lds_dwordx4 v[216:217], off
	s_add_i32 m0, m0, 0x2000
	s_add_u32 s84, s30, 0x80000
	v_lshl_add_u64 v[218:219], s[30:31], 0, v[130:131]
	s_addc_u32 s85, s31, 0
	global_load_lds_dwordx4 v[218:219], off
	s_add_i32 m0, s61, s44
	v_lshl_add_u64 v[220:221], s[84:85], 0, v[134:135]
	global_load_lds_dwordx4 v[220:221], off
	s_add_i32 m0, m0, 0x2000
	v_lshl_add_u64 v[220:221], s[84:85], 0, v[130:131]
	global_load_lds_dwordx4 v[220:221], off
	s_waitcnt vmcnt(6) lgkmcnt(0)
	s_barrier
	s_setprio 1
	v_mfma_f32_16x16x32_bf16 v[62:65], v[146:149], v[184:187], v[62:65]
	v_mfma_f32_16x16x32_bf16 v[58:61], v[160:163], v[184:187], v[58:61]
	v_mfma_f32_16x16x32_bf16 v[46:49], v[146:149], v[192:195], v[46:49]
	v_mfma_f32_16x16x32_bf16 v[42:45], v[160:163], v[192:195], v[42:45]
	v_mfma_f32_16x16x32_bf16 v[30:33], v[146:149], v[200:203], v[30:33]
	v_mfma_f32_16x16x32_bf16 v[26:29], v[160:163], v[200:203], v[26:29]
	v_mfma_f32_16x16x32_bf16 v[14:17], v[146:149], v[208:211], v[14:17]
	v_mfma_f32_16x16x32_bf16 v[10:13], v[160:163], v[208:211], v[10:13]
	v_mfma_f32_16x16x32_bf16 v[62:65], v[150:153], v[188:191], v[62:65]
	v_mfma_f32_16x16x32_bf16 v[58:61], v[164:167], v[188:191], v[58:61]
	v_mfma_f32_16x16x32_bf16 v[46:49], v[150:153], v[196:199], v[46:49]
	v_mfma_f32_16x16x32_bf16 v[42:45], v[164:167], v[196:199], v[42:45]
	v_mfma_f32_16x16x32_bf16 v[30:33], v[150:153], v[204:207], v[30:33]
	v_mfma_f32_16x16x32_bf16 v[26:29], v[164:167], v[204:207], v[26:29]
	v_mfma_f32_16x16x32_bf16 v[14:17], v[150:153], v[212:215], v[14:17]
	v_mfma_f32_16x16x32_bf16 v[10:13], v[164:167], v[212:215], v[10:13]
	s_setprio 0
	s_setprio 1
	v_mfma_f32_16x16x32_bf16 v[54:57], v[168:171], v[184:187], v[54:57]
	v_mfma_f32_16x16x32_bf16 v[50:53], v[176:179], v[184:187], v[50:53]
	v_mfma_f32_16x16x32_bf16 v[38:41], v[168:171], v[192:195], v[38:41]
	v_mfma_f32_16x16x32_bf16 v[34:37], v[176:179], v[192:195], v[34:37]
	v_mfma_f32_16x16x32_bf16 v[22:25], v[168:171], v[200:203], v[22:25]
	v_mfma_f32_16x16x32_bf16 v[18:21], v[176:179], v[200:203], v[18:21]
	v_mfma_f32_16x16x32_bf16 v[6:9], v[168:171], v[208:211], v[6:9]
	v_mfma_f32_16x16x32_bf16 v[2:5], v[176:179], v[208:211], v[2:5]
	v_mfma_f32_16x16x32_bf16 v[54:57], v[172:175], v[188:191], v[54:57]
	v_mfma_f32_16x16x32_bf16 v[50:53], v[180:183], v[188:191], v[50:53]
	v_mfma_f32_16x16x32_bf16 v[38:41], v[172:175], v[196:199], v[38:41]
	v_mfma_f32_16x16x32_bf16 v[34:37], v[180:183], v[196:199], v[34:37]
	v_mfma_f32_16x16x32_bf16 v[22:25], v[172:175], v[204:207], v[22:25]
	v_mfma_f32_16x16x32_bf16 v[18:21], v[180:183], v[204:207], v[18:21]
	v_mfma_f32_16x16x32_bf16 v[6:9], v[172:175], v[212:215], v[6:9]
	v_mfma_f32_16x16x32_bf16 v[2:5], v[180:183], v[212:215], v[2:5]
	s_setprio 0
	s_barrier
; #define PG8_STAGE(bufoff, gbase, voff) do { _Pragma("unroll") for (int _i = 0; _i < 2; ++_i) \
;         __builtin_amdgcn_global_load_lds((const unsigned*)((const char*)(gbase) + (voff)[_i]), (PG8_LAS unsigned*)(lds + (bufoff) + ldsw + _i * 8192), 16, 0, 0); } while (0)
; #define PG8_LDA(dst, b, h) do { _Pragma("unroll") for (int m = 0; m < 4; ++m) _Pragma("unroll") for (int k = 0; k < 2; ++k) dst[m][k] = *(const PG8_LAS bf16x8*)(lds + PG8_SA(b, h) + aoff + m * 2048 + k * 1024); } while (0)
; #define PG8_LDB(dst, b, h) do { _Pragma("unroll") for (int n = 0; n < 2; ++n) _Pragma("unroll") for (int k = 0; k < 2; ++k) dst[n][k] = *(const PG8_LAS bf16x8*)(lds + PG8_SB(b, h) + boff + n * 2048 + k * 1024); } while (0)
; #define PG8_MMA(ai, bj, At, Bt) do { __builtin_amdgcn_s_setprio(1); _Pragma("unroll") for (int m = 0; m < 4; ++m) _Pragma("unroll") for (int n = 0; n < 2; ++n) _Pragma("unroll") for (int k = 0; k < 2; ++k) \
;         acc[ai][bj][m][n] = __builtin_amdgcn_mfma_f32_16x16x32_bf16(Bt[n][k], At[m][k], acc[ai][bj][m][n], 0, 0, 0); __builtin_amdgcn_s_setprio(0); } while (0)
; #define PG8_WAIT_V(n) asm volatile("s_waitcnt vmcnt(" #n ")" ::: "memory")
; #define PG8_WAIT_L(n) asm volatile("s_waitcnt lgkmcnt(" #n ")" ::: "memory")
; #define PG8_BAR __builtin_amdgcn_s_barrier()
; #define PG8_SCHED __builtin_amdgcn_sched_barrier(0)
; template <class Epi, class Sched, bool ALIGN_EPI = false, bool SP2 = false, bool KSEG = false>
; __device__ __forceinline__ void gemm_phase(PG8_LAS unsigned char* lds, const Gemm g, const Sched& S, const Epi& E) {
;     ...
;             PG8_LDB(B0, 1, 0); PG8_LDB(B1, 1, 1); PG8_SCHED; PG8_LDA(At, 1, 0); PG8_STAGE(PG8_SA(0, 1), a2 + hstep, voffA);
;             PG8_WAIT_V(8); PG8_WAIT_L(0); PG8_BAR; PG8_MMA(0, 0, At, B0); PG8_MMA(0, 1, At, B1); PG8_BAR; PG8_SCHED;
	ds_read_b128 v[146:149], v250
	ds_read_b128 v[150:153], v250 offset:1024
	ds_read_b128 v[160:163], v250 offset:2048
	ds_read_b128 v[164:167], v250 offset:3072
	ds_read_b128 v[168:171], v251
	ds_read_b128 v[172:175], v251 offset:1024
	ds_read_b128 v[176:179], v251 offset:2048
	ds_read_b128 v[180:183], v251 offset:3072
	s_mov_b32 m0, s27
	v_lshl_add_u64 v[224:225], s[42:43], 0, v[136:137]
	global_load_lds_dwordx4 v[224:225], off
	s_mov_b32 m0, s47
	v_lshl_add_u64 v[224:225], s[42:43], 0, v[132:133]
	global_load_lds_dwordx4 v[224:225], off
	s_add_u32 s42, s42, 0x80000
	s_addc_u32 s43, s43, 0
	s_mov_b32 m0, s48
	v_lshl_add_u64 v[224:225], s[42:43], 0, v[136:137]
	ds_read_b128 v[184:187], v158 offset:32768
	ds_read_b128 v[188:191], v158 offset:33792
	ds_read_b128 v[192:195], v158 offset:34816
	ds_read_b128 v[196:199], v158 offset:35840
	ds_read_b128 v[200:203], v158 offset:36864
	ds_read_b128 v[204:207], v158 offset:37888
	ds_read_b128 v[208:211], v158 offset:38912
	ds_read_b128 v[212:215], v158 offset:39936
	global_load_lds_dwordx4 v[224:225], off
	s_mov_b32 m0, s49
	v_lshl_add_u64 v[224:225], s[42:43], 0, v[132:133]
	global_load_lds_dwordx4 v[224:225], off
	s_waitcnt vmcnt(8) lgkmcnt(0)
	s_barrier
	s_setprio 1
	v_mfma_f32_16x16x32_bf16 v[126:129], v[146:149], v[184:187], v[126:129]
	v_mfma_f32_16x16x32_bf16 v[122:125], v[160:163], v[184:187], v[122:125]
	v_mfma_f32_16x16x32_bf16 v[110:113], v[146:149], v[192:195], v[110:113]
	v_mfma_f32_16x16x32_bf16 v[106:109], v[160:163], v[192:195], v[106:109]
	v_mfma_f32_16x16x32_bf16 v[94:97], v[146:149], v[200:203], v[94:97]
	v_mfma_f32_16x16x32_bf16 v[90:93], v[160:163], v[200:203], v[90:93]
	v_mfma_f32_16x16x32_bf16 v[78:81], v[146:149], v[208:211], v[78:81]
	v_mfma_f32_16x16x32_bf16 v[74:77], v[160:163], v[208:211], v[74:77]
	v_mfma_f32_16x16x32_bf16 v[126:129], v[150:153], v[188:191], v[126:129]
	v_mfma_f32_16x16x32_bf16 v[122:125], v[164:167], v[188:191], v[122:125]
	v_mfma_f32_16x16x32_bf16 v[110:113], v[150:153], v[196:199], v[110:113]
	v_mfma_f32_16x16x32_bf16 v[106:109], v[164:167], v[196:199], v[106:109]
	v_mfma_f32_16x16x32_bf16 v[94:97], v[150:153], v[204:207], v[94:97]
	v_mfma_f32_16x16x32_bf16 v[90:93], v[164:167], v[204:207], v[90:93]
	v_mfma_f32_16x16x32_bf16 v[78:81], v[150:153], v[212:215], v[78:81]
	v_mfma_f32_16x16x32_bf16 v[74:77], v[164:167], v[212:215], v[74:77]
	s_setprio 0
	s_setprio 1
	v_mfma_f32_16x16x32_bf16 v[118:121], v[168:171], v[184:187], v[118:121]
	v_mfma_f32_16x16x32_bf16 v[114:117], v[176:179], v[184:187], v[114:117]
	v_mfma_f32_16x16x32_bf16 v[102:105], v[168:171], v[192:195], v[102:105]
	v_mfma_f32_16x16x32_bf16 v[98:101], v[176:179], v[192:195], v[98:101]
	v_mfma_f32_16x16x32_bf16 v[86:89], v[168:171], v[200:203], v[86:89]
	v_mfma_f32_16x16x32_bf16 v[82:85], v[176:179], v[200:203], v[82:85]
	v_mfma_f32_16x16x32_bf16 v[70:73], v[168:171], v[208:211], v[70:73]
	v_mfma_f32_16x16x32_bf16 v[66:69], v[176:179], v[208:211], v[66:69]
	v_mfma_f32_16x16x32_bf16 v[118:121], v[172:175], v[188:191], v[118:121]
	v_mfma_f32_16x16x32_bf16 v[114:117], v[180:183], v[188:191], v[114:117]
	v_mfma_f32_16x16x32_bf16 v[102:105], v[172:175], v[196:199], v[102:105]
	v_mfma_f32_16x16x32_bf16 v[98:101], v[180:183], v[196:199], v[98:101]
	v_mfma_f32_16x16x32_bf16 v[86:89], v[172:175], v[204:207], v[86:89]
	v_mfma_f32_16x16x32_bf16 v[82:85], v[180:183], v[204:207], v[82:85]
	v_mfma_f32_16x16x32_bf16 v[70:73], v[172:175], v[212:215], v[70:73]
	v_mfma_f32_16x16x32_bf16 v[66:69], v[180:183], v[212:215], v[66:69]
	s_setprio 0
	s_barrier
; #define PG8_STAGE(bufoff, gbase, voff) do { _Pragma("unroll") for (int _i = 0; _i < 2; ++_i) \
;         __builtin_amdgcn_global_load_lds((const unsigned*)((const char*)(gbase) + (voff)[_i]), (PG8_LAS unsigned*)(lds + (bufoff) + ldsw + _i * 8192), 16, 0, 0); } while (0)
; #define PG8_LDA(dst, b, h) do { _Pragma("unroll") for (int m = 0; m < 4; ++m) _Pragma("unroll") for (int k = 0; k < 2; ++k) dst[m][k] = *(const PG8_LAS bf16x8*)(lds + PG8_SA(b, h) + aoff + m * 2048 + k * 1024); } while (0)
; #define PG8_MMA(ai, bj, At, Bt) do { __builtin_amdgcn_s_setprio(1); _Pragma("unroll") for (int m = 0; m < 4; ++m) _Pragma("unroll") for (int n = 0; n < 2; ++n) _Pragma("unroll") for (int k = 0; k < 2; ++k) \
;         acc[ai][bj][m][n] = __builtin_amdgcn_mfma_f32_16x16x32_bf16(Bt[n][k], At[m][k], acc[ai][bj][m][n], 0, 0, 0); __builtin_amdgcn_s_setprio(0); } while (0)
; #define PG8_WAIT_V(n) asm volatile("s_waitcnt vmcnt(" #n ")" ::: "memory")
; #define PG8_WAIT_L(n) asm volatile("s_waitcnt lgkmcnt(" #n ")" ::: "memory")
; #define PG8_BAR __builtin_amdgcn_s_barrier()
; #define PG8_SCHED __builtin_amdgcn_sched_barrier(0)
; template <class Epi, class Sched, bool ALIGN_EPI = false, bool SP2 = false, bool KSEG = false>
; __device__ __forceinline__ void gemm_phase(PG8_LAS unsigned char* lds, const Gemm g, const Sched& S, const Epi& E) {
;     ...
;         for (int t = 0; t < nt; t += 2) {
;             const bool last = (t == nt - 2);
;             const char* a1 = cA + (size_t)(t + 1) * kstep;
;             const char* a2 = last ? nA : cA + (size_t)(t + 2) * kstep; const char* b2 = last ? nB : cB + (size_t)(t + 2) * kstep;
;             const char* a3 = a2 + kstep; const char* b3 = b2 + kstep;
;     ...
;             PG8_LDA(At, 1, 1); PG8_STAGE(PG8_SB(1, 0), b3, voffB); PG8_STAGE(PG8_SB(1, 1), b3 + hstep, voffB); PG8_STAGE(PG8_SA(1, 0), a3, voffA);
;             PG8_WAIT_V(8); PG8_WAIT_L(0); PG8_BAR; PG8_MMA(1, 0, At, B0); PG8_MMA(1, 1, At, B1); PG8_BAR; PG8_SCHED;
	v_lshl_add_u64 v[216:217], v[216:217], 0, s[12:13]
	s_add_i32 m0, s44, 0x18000
	ds_read_b128 v[184:187], v158 offset:49152
	ds_read_b128 v[188:191], v158 offset:50176
	ds_read_b128 v[192:195], v158 offset:51200
	ds_read_b128 v[196:199], v158 offset:52224
	ds_read_b128 v[200:203], v158 offset:53248
	ds_read_b128 v[204:207], v158 offset:54272
	ds_read_b128 v[208:211], v158 offset:55296
	ds_read_b128 v[212:215], v158 offset:56320
	global_load_lds_dwordx4 v[216:217], off
	s_add_i32 m0, m0, 0x2000
	s_add_u32 s30, s30, 0x80080
	v_lshl_add_u64 v[216:217], v[218:219], 0, s[12:13]
	s_addc_u32 s31, s31, 0
	global_load_lds_dwordx4 v[216:217], off
	s_add_i32 m0, s44, 0x1c000
	v_lshl_add_u64 v[216:217], s[30:31], 0, v[134:135]
	global_load_lds_dwordx4 v[216:217], off
	s_add_i32 m0, m0, 0x2000
	v_lshl_add_u64 v[216:217], s[30:31], 0, v[130:131]
	global_load_lds_dwordx4 v[216:217], off
	s_waitcnt vmcnt(6) lgkmcnt(0)
	s_barrier
	s_setprio 1
	v_mfma_f32_16x16x32_bf16 v[62:65], v[146:149], v[184:187], v[62:65]
	v_mfma_f32_16x16x32_bf16 v[58:61], v[160:163], v[184:187], v[58:61]
	v_mfma_f32_16x16x32_bf16 v[46:49], v[146:149], v[192:195], v[46:49]
	v_mfma_f32_16x16x32_bf16 v[42:45], v[160:163], v[192:195], v[42:45]
	v_mfma_f32_16x16x32_bf16 v[30:33], v[146:149], v[200:203], v[30:33]
	v_mfma_f32_16x16x32_bf16 v[26:29], v[160:163], v[200:203], v[26:29]
	v_mfma_f32_16x16x32_bf16 v[14:17], v[146:149], v[208:211], v[14:17]
	v_mfma_f32_16x16x32_bf16 v[10:13], v[160:163], v[208:211], v[10:13]
	v_mfma_f32_16x16x32_bf16 v[62:65], v[150:153], v[188:191], v[62:65]
	v_mfma_f32_16x16x32_bf16 v[58:61], v[164:167], v[188:191], v[58:61]
	v_mfma_f32_16x16x32_bf16 v[46:49], v[150:153], v[196:199], v[46:49]
	v_mfma_f32_16x16x32_bf16 v[42:45], v[164:167], v[196:199], v[42:45]
	v_mfma_f32_16x16x32_bf16 v[30:33], v[150:153], v[204:207], v[30:33]
	v_mfma_f32_16x16x32_bf16 v[26:29], v[164:167], v[204:207], v[26:29]
	v_mfma_f32_16x16x32_bf16 v[14:17], v[150:153], v[212:215], v[14:17]
	v_mfma_f32_16x16x32_bf16 v[10:13], v[164:167], v[212:215], v[10:13]
	s_setprio 0
	s_setprio 1
	v_mfma_f32_16x16x32_bf16 v[54:57], v[168:171], v[184:187], v[54:57]
	s_add_i32 s80, s80, 2
	v_mfma_f32_16x16x32_bf16 v[50:53], v[176:179], v[184:187], v[50:53]
	s_add_u32 s28, s28, 0x100
	v_mfma_f32_16x16x32_bf16 v[38:41], v[168:171], v[192:195], v[38:41]
	s_addc_u32 s29, s29, 0
	v_mfma_f32_16x16x32_bf16 v[34:37], v[176:179], v[192:195], v[34:37]
	s_add_u32 s66, s66, 0x100
	v_mfma_f32_16x16x32_bf16 v[22:25], v[168:171], v[200:203], v[22:25]
	s_addc_u32 s67, s67, 0
	v_mfma_f32_16x16x32_bf16 v[18:21], v[176:179], v[200:203], v[18:21]
	s_add_u32 s30, s28, 0xfff80080
	v_mfma_f32_16x16x32_bf16 v[6:9], v[168:171], v[208:211], v[6:9]
	s_addc_u32 s31, s29, -1
	v_mfma_f32_16x16x32_bf16 v[2:5], v[176:179], v[208:211], v[2:5]
	s_cmp_eq_u32 s80, 28
	v_mfma_f32_16x16x32_bf16 v[54:57], v[172:175], v[188:191], v[54:57]
	s_cselect_b32 s43, s21, s31
	v_mfma_f32_16x16x32_bf16 v[50:53], v[180:183], v[188:191], v[50:53]
	s_cselect_b32 s42, s64, s30
	v_mfma_f32_16x16x32_bf16 v[38:41], v[172:175], v[196:199], v[38:41]
	s_cselect_b32 s31, s19, s67
	v_mfma_f32_16x16x32_bf16 v[34:37], v[180:183], v[196:199], v[34:37]
	s_cselect_b32 s30, s65, s66
	v_mfma_f32_16x16x32_bf16 v[22:25], v[172:175], v[204:207], v[22:25]
	s_add_u32 s98, s28, 0xfff80000
	v_mfma_f32_16x16x32_bf16 v[18:21], v[180:183], v[204:207], v[18:21]
	s_addc_u32 s99, s29, -1
	v_mfma_f32_16x16x32_bf16 v[6:9], v[172:175], v[212:215], v[6:9]
	s_cmp_gt_u32 s80, 29
	v_mfma_f32_16x16x32_bf16 v[2:5], v[180:183], v[212:215], v[2:5]
	s_setprio 0
	s_barrier
	s_cbranch_scc0 .LBB0_120
	s_and_b64 vcc, exec, s[16:17]
	s_cbranch_vccz .LBB0_123
	s_barrier

; #define PG8_STAGE(bufoff, gbase, voff) do { _Pragma("unroll") for (int _i = 0; _i < 2; ++_i) \
;         __builtin_amdgcn_global_load_lds((const unsigned*)((const char*)(gbase) + (voff)[_i]), (PG8_LAS unsigned*)(lds + (bufoff) + ldsw + _i * 8192), 16, 0, 0); } while (0)
; #define PG8_LDA(dst, b, h) do { _Pragma("unroll") for (int m = 0; m < 4; ++m) _Pragma("unroll") for (int k = 0; k < 2; ++k) dst[m][k] = *(const PG8_LAS bf16x8*)(lds + PG8_SA(b, h) + aoff + m * 2048 + k * 1024); } while (0)
; #define PG8_LDB(dst, b, h) do { _Pragma("unroll") for (int n = 0; n < 2; ++n) _Pragma("unroll") for (int k = 0; k < 2; ++k) dst[n][k] = *(const PG8_LAS bf16x8*)(lds + PG8_SB(b, h) + boff + n * 2048 + k * 1024); } while (0)
; #define PG8_MMA(ai, bj, At, Bt) do { __builtin_amdgcn_s_setprio(1); _Pragma("unroll") for (int m = 0; m < 4; ++m) _Pragma("unroll") for (int n = 0; n < 2; ++n) _Pragma("unroll") for (int k = 0; k < 2; ++k) \
;         acc[ai][bj][m][n] = __builtin_amdgcn_mfma_f32_16x16x32_bf16(Bt[n][k], At[m][k], acc[ai][bj][m][n], 0, 0, 0); __builtin_amdgcn_s_setprio(0); } while (0)
; #define PG8_WAIT_V(n) asm volatile("s_waitcnt vmcnt(" #n ")" ::: "memory")
; #define PG8_WAIT_L(n) asm volatile("s_waitcnt lgkmcnt(" #n ")" ::: "memory")
; #define PG8_BAR __builtin_amdgcn_s_barrier()
; #define PG8_SCHED __builtin_amdgcn_sched_barrier(0)
; template <class Epi, class Sched, bool ALIGN_EPI = false, bool SP2 = false, bool KSEG = false>
; __device__ __forceinline__ void gemm_phase(PG8_LAS unsigned char* lds, const Gemm g, const Sched& S, const Epi& E) {
;     ...
;             PG8_LDB(B0, 0, 0); PG8_LDB(B1, 0, 1); PG8_SCHED; PG8_LDA(At, 0, 0); PG8_STAGE(PG8_SA(1, 1), a1 + hstep, voffA);
;             PG8_WAIT_V(8); PG8_WAIT_L(0); PG8_BAR; PG8_MMA(0, 0, At, B0); PG8_MMA(0, 1, At, B1); PG8_BAR; PG8_SCHED;
;             PG8_LDA(At, 0, 1); PG8_STAGE(PG8_SB(0, 0), b2, voffB); PG8_STAGE(PG8_SB(0, 1), b2 + hstep, voffB); PG8_STAGE(PG8_SA(0, 0), a2, voffA);
;             PG8_WAIT_V(8); PG8_WAIT_L(0); PG8_BAR; PG8_MMA(1, 0, At, B0); PG8_MMA(1, 1, At, B1); PG8_BAR; PG8_SCHED;
.LBB0_497:
	ds_read_b128 v[148:151], v168
	ds_read_b128 v[172:175], v168 offset:1024
	ds_read_b128 v[176:179], v168 offset:2048
	ds_read_b128 v[180:183], v168 offset:3072
	ds_read_b128 v[184:187], v169
	ds_read_b128 v[188:191], v169 offset:1024
	ds_read_b128 v[192:195], v169 offset:2048
	ds_read_b128 v[196:199], v169 offset:3072
	s_mov_b32 m0, s52
	v_lshl_add_u64 v[232:233], s[98:99], 0, v[132:133]
	global_load_lds_dwordx4 v[232:233], off
	s_mov_b32 m0, s53
	v_lshl_add_u64 v[232:233], s[98:99], 0, v[136:137]
	global_load_lds_dwordx4 v[232:233], off
	v_lshl_add_u64 v[232:233], s[36:37], 0, v[140:141]
	s_add_i32 m0, s31, 0xc000
	ds_read_b128 v[200:203], v170
	ds_read_b128 v[204:207], v170 offset:1024
	ds_read_b128 v[208:211], v170 offset:2048
	ds_read_b128 v[212:215], v170 offset:3072
	ds_read_b128 v[216:219], v170 offset:4096
	ds_read_b128 v[220:223], v170 offset:5120
	ds_read_b128 v[224:227], v170 offset:6144
	ds_read_b128 v[228:231], v170 offset:7168
	global_load_lds_dwordx4 v[232:233], off
	s_add_i32 m0, s31, 0xe000
	v_lshl_add_u64 v[232:233], s[36:37], 0, v[142:143]
	global_load_lds_dwordx4 v[232:233], off
	s_waitcnt vmcnt(8) lgkmcnt(0)
	s_barrier
	s_setprio 1
	v_mfma_f32_16x16x32_bf16 v[126:129], v[148:151], v[200:203], v[126:129]
	v_mfma_f32_16x16x32_bf16 v[122:125], v[176:179], v[200:203], v[122:125]
	v_mfma_f32_16x16x32_bf16 v[110:113], v[148:151], v[208:211], v[110:113]
	v_mfma_f32_16x16x32_bf16 v[106:109], v[176:179], v[208:211], v[106:109]
	v_mfma_f32_16x16x32_bf16 v[94:97], v[148:151], v[216:219], v[94:97]
	v_mfma_f32_16x16x32_bf16 v[90:93], v[176:179], v[216:219], v[90:93]
	v_mfma_f32_16x16x32_bf16 v[78:81], v[148:151], v[224:227], v[78:81]
	v_mfma_f32_16x16x32_bf16 v[74:77], v[176:179], v[224:227], v[74:77]
	v_mfma_f32_16x16x32_bf16 v[126:129], v[172:175], v[204:207], v[126:129]
	v_mfma_f32_16x16x32_bf16 v[122:125], v[180:183], v[204:207], v[122:125]
	v_mfma_f32_16x16x32_bf16 v[110:113], v[172:175], v[212:215], v[110:113]
	v_mfma_f32_16x16x32_bf16 v[106:109], v[180:183], v[212:215], v[106:109]
	v_mfma_f32_16x16x32_bf16 v[94:97], v[172:175], v[220:223], v[94:97]
	v_mfma_f32_16x16x32_bf16 v[90:93], v[180:183], v[220:223], v[90:93]
	v_mfma_f32_16x16x32_bf16 v[78:81], v[172:175], v[228:231], v[78:81]
	v_mfma_f32_16x16x32_bf16 v[74:77], v[180:183], v[228:231], v[74:77]
	s_setprio 0
	s_setprio 1
	v_mfma_f32_16x16x32_bf16 v[118:121], v[184:187], v[200:203], v[118:121]
	v_mfma_f32_16x16x32_bf16 v[114:117], v[192:195], v[200:203], v[114:117]
	v_mfma_f32_16x16x32_bf16 v[102:105], v[184:187], v[208:211], v[102:105]
	v_mfma_f32_16x16x32_bf16 v[98:101], v[192:195], v[208:211], v[98:101]
	v_mfma_f32_16x16x32_bf16 v[86:89], v[184:187], v[216:219], v[86:89]
	v_mfma_f32_16x16x32_bf16 v[82:85], v[192:195], v[216:219], v[82:85]
	v_mfma_f32_16x16x32_bf16 v[70:73], v[184:187], v[224:227], v[70:73]
	v_mfma_f32_16x16x32_bf16 v[66:69], v[192:195], v[224:227], v[66:69]
	v_mfma_f32_16x16x32_bf16 v[118:121], v[188:191], v[204:207], v[118:121]
	v_mfma_f32_16x16x32_bf16 v[114:117], v[196:199], v[204:207], v[114:117]
	v_mfma_f32_16x16x32_bf16 v[102:105], v[188:191], v[212:215], v[102:105]
	v_mfma_f32_16x16x32_bf16 v[98:101], v[196:199], v[212:215], v[98:101]
	v_mfma_f32_16x16x32_bf16 v[86:89], v[188:191], v[220:223], v[86:89]
	v_mfma_f32_16x16x32_bf16 v[82:85], v[196:199], v[220:223], v[82:85]
	v_mfma_f32_16x16x32_bf16 v[70:73], v[188:191], v[228:231], v[70:73]
	v_mfma_f32_16x16x32_bf16 v[66:69], v[196:199], v[228:231], v[66:69]
	s_setprio 0
	s_barrier
	v_lshl_add_u64 v[232:233], s[38:39], 0, v[134:135]
	s_add_i32 m0, s54, s43
	ds_read_b128 v[200:203], v170 offset:16384
	ds_read_b128 v[204:207], v170 offset:17408
	ds_read_b128 v[208:211], v170 offset:18432
	ds_read_b128 v[212:215], v170 offset:19456
	ds_read_b128 v[216:219], v170 offset:20480
	ds_read_b128 v[220:223], v170 offset:21504
	ds_read_b128 v[224:227], v170 offset:22528
	ds_read_b128 v[228:231], v170 offset:23552
	global_load_lds_dwordx4 v[232:233], off
	s_add_i32 m0, m0, 0x2000
	s_add_u32 s64, s38, 0x80000
	v_lshl_add_u64 v[234:235], s[38:39], 0, v[138:139]
	s_addc_u32 s65, s39, 0
	global_load_lds_dwordx4 v[234:235], off
	s_add_i32 m0, s55, s43
	v_lshl_add_u64 v[236:237], s[64:65], 0, v[134:135]
	global_load_lds_dwordx4 v[236:237], off
	s_add_i32 m0, m0, 0x2000
	v_lshl_add_u64 v[236:237], s[64:65], 0, v[138:139]
	global_load_lds_dwordx4 v[236:237], off
	s_waitcnt vmcnt(6) lgkmcnt(0)
	s_barrier
	s_setprio 1
	v_mfma_f32_16x16x32_bf16 v[62:65], v[148:151], v[200:203], v[62:65]
	v_mfma_f32_16x16x32_bf16 v[58:61], v[176:179], v[200:203], v[58:61]
	v_mfma_f32_16x16x32_bf16 v[46:49], v[148:151], v[208:211], v[46:49]
	v_mfma_f32_16x16x32_bf16 v[42:45], v[176:179], v[208:211], v[42:45]
	v_mfma_f32_16x16x32_bf16 v[30:33], v[148:151], v[216:219], v[30:33]
	v_mfma_f32_16x16x32_bf16 v[26:29], v[176:179], v[216:219], v[26:29]
	v_mfma_f32_16x16x32_bf16 v[14:17], v[148:151], v[224:227], v[14:17]
	v_mfma_f32_16x16x32_bf16 v[10:13], v[176:179], v[224:227], v[10:13]
	v_mfma_f32_16x16x32_bf16 v[62:65], v[172:175], v[204:207], v[62:65]
	v_mfma_f32_16x16x32_bf16 v[58:61], v[180:183], v[204:207], v[58:61]
	v_mfma_f32_16x16x32_bf16 v[46:49], v[172:175], v[212:215], v[46:49]
	v_mfma_f32_16x16x32_bf16 v[42:45], v[180:183], v[212:215], v[42:45]
	v_mfma_f32_16x16x32_bf16 v[30:33], v[172:175], v[220:223], v[30:33]
	v_mfma_f32_16x16x32_bf16 v[26:29], v[180:183], v[220:223], v[26:29]
	v_mfma_f32_16x16x32_bf16 v[14:17], v[172:175], v[228:231], v[14:17]
	v_mfma_f32_16x16x32_bf16 v[10:13], v[180:183], v[228:231], v[10:13]
	s_setprio 0
	s_setprio 1
	v_mfma_f32_16x16x32_bf16 v[54:57], v[184:187], v[200:203], v[54:57]
	v_mfma_f32_16x16x32_bf16 v[50:53], v[192:195], v[200:203], v[50:53]
	v_mfma_f32_16x16x32_bf16 v[38:41], v[184:187], v[208:211], v[38:41]
	v_mfma_f32_16x16x32_bf16 v[34:37], v[192:195], v[208:211], v[34:37]
	v_mfma_f32_16x16x32_bf16 v[22:25], v[184:187], v[216:219], v[22:25]
	v_mfma_f32_16x16x32_bf16 v[18:21], v[192:195], v[216:219], v[18:21]
	v_mfma_f32_16x16x32_bf16 v[6:9], v[184:187], v[224:227], v[6:9]
	v_mfma_f32_16x16x32_bf16 v[2:5], v[192:195], v[224:227], v[2:5]
	v_mfma_f32_16x16x32_bf16 v[54:57], v[188:191], v[204:207], v[54:57]
	v_mfma_f32_16x16x32_bf16 v[50:53], v[196:199], v[204:207], v[50:53]
	v_mfma_f32_16x16x32_bf16 v[38:41], v[188:191], v[212:215], v[38:41]
	v_mfma_f32_16x16x32_bf16 v[34:37], v[196:199], v[212:215], v[34:37]
	v_mfma_f32_16x16x32_bf16 v[22:25], v[188:191], v[220:223], v[22:25]
	v_mfma_f32_16x16x32_bf16 v[18:21], v[196:199], v[220:223], v[18:21]
	v_mfma_f32_16x16x32_bf16 v[6:9], v[188:191], v[228:231], v[6:9]
	v_mfma_f32_16x16x32_bf16 v[2:5], v[196:199], v[228:231], v[2:5]
	s_setprio 0
	s_barrier
; #define PG8_STAGE(bufoff, gbase, voff) do { _Pragma("unroll") for (int _i = 0; _i < 2; ++_i) \
;         __builtin_amdgcn_global_load_lds((const unsigned*)((const char*)(gbase) + (voff)[_i]), (PG8_LAS unsigned*)(lds + (bufoff) + ldsw + _i * 8192), 16, 0, 0); } while (0)
; #define PG8_LDA(dst, b, h) do { _Pragma("unroll") for (int m = 0; m < 4; ++m) _Pragma("unroll") for (int k = 0; k < 2; ++k) dst[m][k] = *(const PG8_LAS bf16x8*)(lds + PG8_SA(b, h) + aoff + m * 2048 + k * 1024); } while (0)
; #define PG8_LDB(dst, b, h) do { _Pragma("unroll") for (int n = 0; n < 2; ++n) _Pragma("unroll") for (int k = 0; k < 2; ++k) dst[n][k] = *(const PG8_LAS bf16x8*)(lds + PG8_SB(b, h) + boff + n * 2048 + k * 1024); } while (0)
; #define PG8_MMA(ai, bj, At, Bt) do { __builtin_amdgcn_s_setprio(1); _Pragma("unroll") for (int m = 0; m < 4; ++m) _Pragma("unroll") for (int n = 0; n < 2; ++n) _Pragma("unroll") for (int k = 0; k < 2; ++k) \
;         acc[ai][bj][m][n] = __builtin_amdgcn_mfma_f32_16x16x32_bf16(Bt[n][k], At[m][k], acc[ai][bj][m][n], 0, 0, 0); __builtin_amdgcn_s_setprio(0); } while (0)
; #define PG8_WAIT_V(n) asm volatile("s_waitcnt vmcnt(" #n ")" ::: "memory")
; #define PG8_WAIT_L(n) asm volatile("s_waitcnt lgkmcnt(" #n ")" ::: "memory")
; #define PG8_BAR __builtin_amdgcn_s_barrier()
; #define PG8_SCHED __builtin_amdgcn_sched_barrier(0)
; template <class Epi, class Sched, bool ALIGN_EPI = false, bool SP2 = false, bool KSEG = false>
; __device__ __forceinline__ void gemm_phase(PG8_LAS unsigned char* lds, const Gemm g, const Sched& S, const Epi& E) {
;     ...
;             PG8_LDB(B0, 1, 0); PG8_LDB(B1, 1, 1); PG8_SCHED; PG8_LDA(At, 1, 0); PG8_STAGE(PG8_SA(0, 1), a2 + hstep, voffA);
;             PG8_WAIT_V(8); PG8_WAIT_L(0); PG8_BAR; PG8_MMA(0, 0, At, B0); PG8_MMA(0, 1, At, B1); PG8_BAR; PG8_SCHED;
	ds_read_b128 v[148:151], v250
	ds_read_b128 v[172:175], v250 offset:1024
	ds_read_b128 v[176:179], v250 offset:2048
	ds_read_b128 v[180:183], v250 offset:3072
	ds_read_b128 v[184:187], v251
	ds_read_b128 v[188:191], v251 offset:1024
	ds_read_b128 v[192:195], v251 offset:2048
	ds_read_b128 v[196:199], v251 offset:3072
	s_mov_b32 m0, s31
	v_lshl_add_u64 v[240:241], s[40:41], 0, v[132:133]
	global_load_lds_dwordx4 v[240:241], off
	s_mov_b32 m0, s45
	v_lshl_add_u64 v[240:241], s[40:41], 0, v[136:137]
	global_load_lds_dwordx4 v[240:241], off
	s_add_u32 s40, s40, 0x80000
	s_addc_u32 s41, s41, 0
	s_mov_b32 m0, s49
	v_lshl_add_u64 v[240:241], s[40:41], 0, v[132:133]
	ds_read_b128 v[200:203], v170 offset:32768
	ds_read_b128 v[204:207], v170 offset:33792
	ds_read_b128 v[208:211], v170 offset:34816
	ds_read_b128 v[212:215], v170 offset:35840
	ds_read_b128 v[216:219], v170 offset:36864
	ds_read_b128 v[220:223], v170 offset:37888
	ds_read_b128 v[224:227], v170 offset:38912
	ds_read_b128 v[228:231], v170 offset:39936
	global_load_lds_dwordx4 v[240:241], off
	s_mov_b32 m0, s50
	v_lshl_add_u64 v[240:241], s[40:41], 0, v[136:137]
	global_load_lds_dwordx4 v[240:241], off
	s_waitcnt vmcnt(8) lgkmcnt(0)
	s_barrier
	s_setprio 1
	v_mfma_f32_16x16x32_bf16 v[126:129], v[148:151], v[200:203], v[126:129]
	v_mfma_f32_16x16x32_bf16 v[122:125], v[176:179], v[200:203], v[122:125]
	v_mfma_f32_16x16x32_bf16 v[110:113], v[148:151], v[208:211], v[110:113]
	v_mfma_f32_16x16x32_bf16 v[106:109], v[176:179], v[208:211], v[106:109]
	v_mfma_f32_16x16x32_bf16 v[94:97], v[148:151], v[216:219], v[94:97]
	v_mfma_f32_16x16x32_bf16 v[90:93], v[176:179], v[216:219], v[90:93]
	v_mfma_f32_16x16x32_bf16 v[78:81], v[148:151], v[224:227], v[78:81]
	v_mfma_f32_16x16x32_bf16 v[74:77], v[176:179], v[224:227], v[74:77]
	v_mfma_f32_16x16x32_bf16 v[126:129], v[172:175], v[204:207], v[126:129]
	v_mfma_f32_16x16x32_bf16 v[122:125], v[180:183], v[204:207], v[122:125]
	v_mfma_f32_16x16x32_bf16 v[110:113], v[172:175], v[212:215], v[110:113]
	v_mfma_f32_16x16x32_bf16 v[106:109], v[180:183], v[212:215], v[106:109]
	v_mfma_f32_16x16x32_bf16 v[94:97], v[172:175], v[220:223], v[94:97]
	v_mfma_f32_16x16x32_bf16 v[90:93], v[180:183], v[220:223], v[90:93]
	v_mfma_f32_16x16x32_bf16 v[78:81], v[172:175], v[228:231], v[78:81]
	v_mfma_f32_16x16x32_bf16 v[74:77], v[180:183], v[228:231], v[74:77]
	s_setprio 0
	s_setprio 1
	v_mfma_f32_16x16x32_bf16 v[118:121], v[184:187], v[200:203], v[118:121]
	v_mfma_f32_16x16x32_bf16 v[114:117], v[192:195], v[200:203], v[114:117]
	v_mfma_f32_16x16x32_bf16 v[102:105], v[184:187], v[208:211], v[102:105]
	v_mfma_f32_16x16x32_bf16 v[98:101], v[192:195], v[208:211], v[98:101]
	v_mfma_f32_16x16x32_bf16 v[86:89], v[184:187], v[216:219], v[86:89]
	v_mfma_f32_16x16x32_bf16 v[82:85], v[192:195], v[216:219], v[82:85]
	v_mfma_f32_16x16x32_bf16 v[70:73], v[184:187], v[224:227], v[70:73]
	v_mfma_f32_16x16x32_bf16 v[66:69], v[192:195], v[224:227], v[66:69]
	v_mfma_f32_16x16x32_bf16 v[118:121], v[188:191], v[204:207], v[118:121]
	v_mfma_f32_16x16x32_bf16 v[114:117], v[196:199], v[204:207], v[114:117]
	v_mfma_f32_16x16x32_bf16 v[102:105], v[188:191], v[212:215], v[102:105]
	v_mfma_f32_16x16x32_bf16 v[98:101], v[196:199], v[212:215], v[98:101]
	v_mfma_f32_16x16x32_bf16 v[86:89], v[188:191], v[220:223], v[86:89]
	v_mfma_f32_16x16x32_bf16 v[82:85], v[196:199], v[220:223], v[82:85]
	v_mfma_f32_16x16x32_bf16 v[70:73], v[188:191], v[228:231], v[70:73]
	v_mfma_f32_16x16x32_bf16 v[66:69], v[196:199], v[228:231], v[66:69]
	s_setprio 0
	s_barrier
; #define PG8_STAGE(bufoff, gbase, voff) do { _Pragma("unroll") for (int _i = 0; _i < 2; ++_i) \
;         __builtin_amdgcn_global_load_lds((const unsigned*)((const char*)(gbase) + (voff)[_i]), (PG8_LAS unsigned*)(lds + (bufoff) + ldsw + _i * 8192), 16, 0, 0); } while (0)
; #define PG8_LDA(dst, b, h) do { _Pragma("unroll") for (int m = 0; m < 4; ++m) _Pragma("unroll") for (int k = 0; k < 2; ++k) dst[m][k] = *(const PG8_LAS bf16x8*)(lds + PG8_SA(b, h) + aoff + m * 2048 + k * 1024); } while (0)
; #define PG8_MMA(ai, bj, At, Bt) do { __builtin_amdgcn_s_setprio(1); _Pragma("unroll") for (int m = 0; m < 4; ++m) _Pragma("unroll") for (int n = 0; n < 2; ++n) _Pragma("unroll") for (int k = 0; k < 2; ++k) \
;         acc[ai][bj][m][n] = __builtin_amdgcn_mfma_f32_16x16x32_bf16(Bt[n][k], At[m][k], acc[ai][bj][m][n], 0, 0, 0); __builtin_amdgcn_s_setprio(0); } while (0)
; #define PG8_WAIT_V(n) asm volatile("s_waitcnt vmcnt(" #n ")" ::: "memory")
; #define PG8_WAIT_L(n) asm volatile("s_waitcnt lgkmcnt(" #n ")" ::: "memory")
; #define PG8_BAR __builtin_amdgcn_s_barrier()
; #define PG8_SCHED __builtin_amdgcn_sched_barrier(0)
; template <class Epi, class Sched, bool ALIGN_EPI = false, bool SP2 = false, bool KSEG = false>
; __device__ __forceinline__ void gemm_phase(PG8_LAS unsigned char* lds, const Gemm g, const Sched& S, const Epi& E) {
;     ...
;         for (int t = 0; t < nt; t += 2) {
;             const bool last = (t == nt - 2);
;             const char* a1 = cA + (size_t)(t + 1) * kstep;
;             const char* a2 = last ? nA : cA + (size_t)(t + 2) * kstep; const char* b2 = last ? nB : cB + (size_t)(t + 2) * kstep;
;             const char* a3 = a2 + kstep; const char* b3 = b2 + kstep;
;     ...
;             PG8_LDA(At, 1, 1); PG8_STAGE(PG8_SB(1, 0), b3, voffB); PG8_STAGE(PG8_SB(1, 1), b3 + hstep, voffB); PG8_STAGE(PG8_SA(1, 0), a3, voffA);
;             PG8_WAIT_V(8); PG8_WAIT_L(0); PG8_BAR; PG8_MMA(1, 0, At, B0); PG8_MMA(1, 1, At, B1); PG8_BAR; PG8_SCHED;
	v_lshl_add_u64 v[232:233], v[232:233], 0, s[10:11]
	s_add_i32 m0, s43, 0x18000
	ds_read_b128 v[200:203], v170 offset:49152
	ds_read_b128 v[204:207], v170 offset:50176
	ds_read_b128 v[208:211], v170 offset:51200
	ds_read_b128 v[212:215], v170 offset:52224
	ds_read_b128 v[216:219], v170 offset:53248
	ds_read_b128 v[220:223], v170 offset:54272
	ds_read_b128 v[224:227], v170 offset:55296
	ds_read_b128 v[228:231], v170 offset:56320
	global_load_lds_dwordx4 v[232:233], off
	s_add_i32 m0, m0, 0x2000
	s_add_u32 s38, s38, 0x80080
	v_lshl_add_u64 v[232:233], v[234:235], 0, s[10:11]
	s_addc_u32 s39, s39, 0
	global_load_lds_dwordx4 v[232:233], off
	s_add_i32 m0, s43, 0x1c000
	v_lshl_add_u64 v[232:233], s[38:39], 0, v[134:135]
	global_load_lds_dwordx4 v[232:233], off
	s_add_i32 m0, m0, 0x2000
	v_lshl_add_u64 v[232:233], s[38:39], 0, v[138:139]
	global_load_lds_dwordx4 v[232:233], off
	s_waitcnt vmcnt(6) lgkmcnt(0)
	s_barrier
	s_setprio 1
	v_mfma_f32_16x16x32_bf16 v[62:65], v[148:151], v[200:203], v[62:65]
	v_mfma_f32_16x16x32_bf16 v[58:61], v[176:179], v[200:203], v[58:61]
	v_mfma_f32_16x16x32_bf16 v[46:49], v[148:151], v[208:211], v[46:49]
	v_mfma_f32_16x16x32_bf16 v[42:45], v[176:179], v[208:211], v[42:45]
	v_mfma_f32_16x16x32_bf16 v[30:33], v[148:151], v[216:219], v[30:33]
	v_mfma_f32_16x16x32_bf16 v[26:29], v[176:179], v[216:219], v[26:29]
	v_mfma_f32_16x16x32_bf16 v[14:17], v[148:151], v[224:227], v[14:17]
	v_mfma_f32_16x16x32_bf16 v[10:13], v[176:179], v[224:227], v[10:13]
	v_mfma_f32_16x16x32_bf16 v[62:65], v[172:175], v[204:207], v[62:65]
	v_mfma_f32_16x16x32_bf16 v[58:61], v[180:183], v[204:207], v[58:61]
	v_mfma_f32_16x16x32_bf16 v[46:49], v[172:175], v[212:215], v[46:49]
	v_mfma_f32_16x16x32_bf16 v[42:45], v[180:183], v[212:215], v[42:45]
	v_mfma_f32_16x16x32_bf16 v[30:33], v[172:175], v[220:223], v[30:33]
	v_mfma_f32_16x16x32_bf16 v[26:29], v[180:183], v[220:223], v[26:29]
	v_mfma_f32_16x16x32_bf16 v[14:17], v[172:175], v[228:231], v[14:17]
	v_mfma_f32_16x16x32_bf16 v[10:13], v[180:183], v[228:231], v[10:13]
	s_setprio 0
	s_setprio 1
	v_mfma_f32_16x16x32_bf16 v[54:57], v[184:187], v[200:203], v[54:57]
	s_add_i32 s62, s62, 2
	v_mfma_f32_16x16x32_bf16 v[50:53], v[192:195], v[200:203], v[50:53]
	s_add_u32 s36, s36, 0x100
	v_mfma_f32_16x16x32_bf16 v[38:41], v[184:187], v[208:211], v[38:41]
	s_addc_u32 s37, s37, 0
	v_mfma_f32_16x16x32_bf16 v[34:37], v[192:195], v[208:211], v[34:37]
	s_add_u32 s60, s60, 0x100
	v_mfma_f32_16x16x32_bf16 v[22:25], v[184:187], v[216:219], v[22:25]
	s_addc_u32 s61, s61, 0
	v_mfma_f32_16x16x32_bf16 v[18:21], v[192:195], v[216:219], v[18:21]
	s_add_u32 s33, s36, 0xfff80080
	v_mfma_f32_16x16x32_bf16 v[6:9], v[184:187], v[224:227], v[6:9]
	s_addc_u32 s38, s37, -1
	v_mfma_f32_16x16x32_bf16 v[2:5], v[192:195], v[224:227], v[2:5]
	s_cmp_eq_u32 s62, 28
	v_mfma_f32_16x16x32_bf16 v[54:57], v[188:191], v[204:207], v[54:57]
	s_cselect_b32 s41, s25, s38
	v_mfma_f32_16x16x32_bf16 v[50:53], v[196:199], v[204:207], v[50:53]
	s_cselect_b32 s40, s58, s33
	v_mfma_f32_16x16x32_bf16 v[38:41], v[188:191], v[212:215], v[38:41]
	s_cselect_b32 s39, s23, s61
	v_mfma_f32_16x16x32_bf16 v[34:37], v[196:199], v[212:215], v[34:37]
	s_cselect_b32 s38, s59, s60
	v_mfma_f32_16x16x32_bf16 v[22:25], v[188:191], v[220:223], v[22:25]
	s_add_u32 s98, s36, 0xfff80000
	v_mfma_f32_16x16x32_bf16 v[18:21], v[196:199], v[220:223], v[18:21]
	s_addc_u32 s99, s37, -1
	v_mfma_f32_16x16x32_bf16 v[6:9], v[188:191], v[228:231], v[6:9]
	s_cmp_gt_u32 s62, 29
	v_mfma_f32_16x16x32_bf16 v[2:5], v[196:199], v[228:231], v[2:5]
	s_setprio 0
	s_barrier
	s_cbranch_scc0 .LBB0_497
	s_and_b64 vcc, exec, s[12:13]
	s_cbranch_vccz .LBB0_500
	s_barrier

; #define PG8_STAGE(bufoff, gbase, voff) do { _Pragma("unroll") for (int _i = 0; _i < 2; ++_i) \
;         __builtin_amdgcn_global_load_lds((const unsigned*)((const char*)(gbase) + (voff)[_i]), (PG8_LAS unsigned*)(lds + (bufoff) + ldsw + _i * 8192), 16, 0, 0); } while (0)
; #define PG8_LDA(dst, b, h) do { _Pragma("unroll") for (int m = 0; m < 4; ++m) _Pragma("unroll") for (int k = 0; k < 2; ++k) dst[m][k] = *(const PG8_LAS bf16x8*)(lds + PG8_SA(b, h) + aoff + m * 2048 + k * 1024); } while (0)
; #define PG8_LDB(dst, b, h) do { _Pragma("unroll") for (int n = 0; n < 2; ++n) _Pragma("unroll") for (int k = 0; k < 2; ++k) dst[n][k] = *(const PG8_LAS bf16x8*)(lds + PG8_SB(b, h) + boff + n * 2048 + k * 1024); } while (0)
; #define PG8_MMA(ai, bj, At, Bt) do { __builtin_amdgcn_s_setprio(1); _Pragma("unroll") for (int m = 0; m < 4; ++m) _Pragma("unroll") for (int n = 0; n < 2; ++n) _Pragma("unroll") for (int k = 0; k < 2; ++k) \
;         acc[ai][bj][m][n] = __builtin_amdgcn_mfma_f32_16x16x32_bf16(Bt[n][k], At[m][k], acc[ai][bj][m][n], 0, 0, 0); __builtin_amdgcn_s_setprio(0); } while (0)
; #define PG8_WAIT_V(n) asm volatile("s_waitcnt vmcnt(" #n ")" ::: "memory")
; #define PG8_WAIT_L(n) asm volatile("s_waitcnt lgkmcnt(" #n ")" ::: "memory")
; #define PG8_BAR __builtin_amdgcn_s_barrier()
; #define PG8_SCHED __builtin_amdgcn_sched_barrier(0)
; template <class Epi, class Sched, bool ALIGN_EPI = false, bool SP2 = false, bool KSEG = false>
; __device__ __forceinline__ void gemm_phase(PG8_LAS unsigned char* lds, const Gemm g, const Sched& S, const Epi& E) {
;     ...
;             PG8_LDB(B0, 0, 0); PG8_LDB(B1, 0, 1); PG8_SCHED; PG8_LDA(At, 0, 0); PG8_STAGE(PG8_SA(1, 1), a1 + hstep, voffA);
;             PG8_WAIT_V(8); PG8_WAIT_L(0); PG8_BAR; PG8_MMA(0, 0, At, B0); PG8_MMA(0, 1, At, B1); PG8_BAR; PG8_SCHED;
;             PG8_LDA(At, 0, 1); PG8_STAGE(PG8_SB(0, 0), b2, voffB); PG8_STAGE(PG8_SB(0, 1), b2 + hstep, voffB); PG8_STAGE(PG8_SA(0, 0), a2, voffA);
;             PG8_WAIT_V(8); PG8_WAIT_L(0); PG8_BAR; PG8_MMA(1, 0, At, B0); PG8_MMA(1, 1, At, B1); PG8_BAR; PG8_SCHED;
.LBB0_537:
	ds_read_b128 v[154:157], v173
	ds_read_b128 v[176:179], v173 offset:1024
	ds_read_b128 v[180:183], v173 offset:2048
	ds_read_b128 v[184:187], v173 offset:3072
	ds_read_b128 v[188:191], v174
	ds_read_b128 v[192:195], v174 offset:1024
	ds_read_b128 v[196:199], v174 offset:2048
	ds_read_b128 v[200:203], v174 offset:3072
	s_mov_b32 m0, s54
	v_lshl_add_u64 v[236:237], s[98:99], 0, v[140:141]
	global_load_lds_dwordx4 v[236:237], off
	s_mov_b32 m0, s55
	v_lshl_add_u64 v[236:237], s[98:99], 0, v[142:143]
	global_load_lds_dwordx4 v[236:237], off
	v_lshl_add_u64 v[236:237], s[36:37], 0, v[146:147]
	s_add_i32 m0, s44, 0xc000
	ds_read_b128 v[204:207], v175
	ds_read_b128 v[208:211], v175 offset:1024
	ds_read_b128 v[212:215], v175 offset:2048
	ds_read_b128 v[216:219], v175 offset:3072
	ds_read_b128 v[220:223], v175 offset:4096
	ds_read_b128 v[224:227], v175 offset:5120
	ds_read_b128 v[228:231], v175 offset:6144
	ds_read_b128 v[232:235], v175 offset:7168
	global_load_lds_dwordx4 v[236:237], off
	s_add_i32 m0, s44, 0xe000
	v_lshl_add_u64 v[236:237], s[36:37], 0, v[148:149]
	global_load_lds_dwordx4 v[236:237], off
	s_waitcnt vmcnt(8) lgkmcnt(0)
	s_barrier
	s_setprio 1
	v_mfma_f32_16x16x32_bf16 v[126:129], v[154:157], v[204:207], v[126:129]
	v_mfma_f32_16x16x32_bf16 v[122:125], v[180:183], v[204:207], v[122:125]
	v_mfma_f32_16x16x32_bf16 v[110:113], v[154:157], v[212:215], v[110:113]
	v_mfma_f32_16x16x32_bf16 v[106:109], v[180:183], v[212:215], v[106:109]
	v_mfma_f32_16x16x32_bf16 v[94:97], v[154:157], v[220:223], v[94:97]
	v_mfma_f32_16x16x32_bf16 v[90:93], v[180:183], v[220:223], v[90:93]
	v_mfma_f32_16x16x32_bf16 v[78:81], v[154:157], v[228:231], v[78:81]
	v_mfma_f32_16x16x32_bf16 v[74:77], v[180:183], v[228:231], v[74:77]
	v_mfma_f32_16x16x32_bf16 v[126:129], v[176:179], v[208:211], v[126:129]
	v_mfma_f32_16x16x32_bf16 v[122:125], v[184:187], v[208:211], v[122:125]
	v_mfma_f32_16x16x32_bf16 v[110:113], v[176:179], v[216:219], v[110:113]
	v_mfma_f32_16x16x32_bf16 v[106:109], v[184:187], v[216:219], v[106:109]
	v_mfma_f32_16x16x32_bf16 v[94:97], v[176:179], v[224:227], v[94:97]
	v_mfma_f32_16x16x32_bf16 v[90:93], v[184:187], v[224:227], v[90:93]
	v_mfma_f32_16x16x32_bf16 v[78:81], v[176:179], v[232:235], v[78:81]
	v_mfma_f32_16x16x32_bf16 v[74:77], v[184:187], v[232:235], v[74:77]
	s_setprio 0
	s_setprio 1
	v_mfma_f32_16x16x32_bf16 v[118:121], v[188:191], v[204:207], v[118:121]
	v_mfma_f32_16x16x32_bf16 v[114:117], v[196:199], v[204:207], v[114:117]
	v_mfma_f32_16x16x32_bf16 v[102:105], v[188:191], v[212:215], v[102:105]
	v_mfma_f32_16x16x32_bf16 v[98:101], v[196:199], v[212:215], v[98:101]
	v_mfma_f32_16x16x32_bf16 v[86:89], v[188:191], v[220:223], v[86:89]
	v_mfma_f32_16x16x32_bf16 v[82:85], v[196:199], v[220:223], v[82:85]
	v_mfma_f32_16x16x32_bf16 v[70:73], v[188:191], v[228:231], v[70:73]
	v_mfma_f32_16x16x32_bf16 v[66:69], v[196:199], v[228:231], v[66:69]
	v_mfma_f32_16x16x32_bf16 v[118:121], v[192:195], v[208:211], v[118:121]
	v_mfma_f32_16x16x32_bf16 v[114:117], v[200:203], v[208:211], v[114:117]
	v_mfma_f32_16x16x32_bf16 v[102:105], v[192:195], v[216:219], v[102:105]
	v_mfma_f32_16x16x32_bf16 v[98:101], v[200:203], v[216:219], v[98:101]
	v_mfma_f32_16x16x32_bf16 v[86:89], v[192:195], v[224:227], v[86:89]
	v_mfma_f32_16x16x32_bf16 v[82:85], v[200:203], v[224:227], v[82:85]
	v_mfma_f32_16x16x32_bf16 v[70:73], v[192:195], v[232:235], v[70:73]
	v_mfma_f32_16x16x32_bf16 v[66:69], v[200:203], v[232:235], v[66:69]
	s_setprio 0
	s_barrier
	v_lshl_add_u64 v[236:237], s[38:39], 0, v[130:131]
	s_add_i32 m0, s56, s43
	ds_read_b128 v[204:207], v175 offset:16384
	ds_read_b128 v[208:211], v175 offset:17408
	ds_read_b128 v[212:215], v175 offset:18432
	ds_read_b128 v[216:219], v175 offset:19456
	ds_read_b128 v[220:223], v175 offset:20480
	ds_read_b128 v[224:227], v175 offset:21504
	ds_read_b128 v[228:231], v175 offset:22528
	ds_read_b128 v[232:235], v175 offset:23552
	global_load_lds_dwordx4 v[236:237], off
	s_add_i32 m0, m0, 0x2000
	s_add_u32 s66, s38, 0x160000
	v_lshl_add_u64 v[238:239], s[38:39], 0, v[144:145]
	s_addc_u32 s67, s39, 0
	global_load_lds_dwordx4 v[238:239], off
	s_add_i32 m0, s57, s43
	v_lshl_add_u64 v[240:241], s[66:67], 0, v[130:131]
	global_load_lds_dwordx4 v[240:241], off
	s_add_i32 m0, m0, 0x2000
	v_lshl_add_u64 v[240:241], s[66:67], 0, v[144:145]
	global_load_lds_dwordx4 v[240:241], off
	s_waitcnt vmcnt(6) lgkmcnt(0)
	s_barrier
	s_setprio 1
	v_mfma_f32_16x16x32_bf16 v[62:65], v[154:157], v[204:207], v[62:65]
	v_mfma_f32_16x16x32_bf16 v[58:61], v[180:183], v[204:207], v[58:61]
	v_mfma_f32_16x16x32_bf16 v[46:49], v[154:157], v[212:215], v[46:49]
	v_mfma_f32_16x16x32_bf16 v[42:45], v[180:183], v[212:215], v[42:45]
	v_mfma_f32_16x16x32_bf16 v[30:33], v[154:157], v[220:223], v[30:33]
	v_mfma_f32_16x16x32_bf16 v[26:29], v[180:183], v[220:223], v[26:29]
	v_mfma_f32_16x16x32_bf16 v[14:17], v[154:157], v[228:231], v[14:17]
	v_mfma_f32_16x16x32_bf16 v[10:13], v[180:183], v[228:231], v[10:13]
	v_mfma_f32_16x16x32_bf16 v[62:65], v[176:179], v[208:211], v[62:65]
	v_mfma_f32_16x16x32_bf16 v[58:61], v[184:187], v[208:211], v[58:61]
	v_mfma_f32_16x16x32_bf16 v[46:49], v[176:179], v[216:219], v[46:49]
	v_mfma_f32_16x16x32_bf16 v[42:45], v[184:187], v[216:219], v[42:45]
	v_mfma_f32_16x16x32_bf16 v[30:33], v[176:179], v[224:227], v[30:33]
	v_mfma_f32_16x16x32_bf16 v[26:29], v[184:187], v[224:227], v[26:29]
	v_mfma_f32_16x16x32_bf16 v[14:17], v[176:179], v[232:235], v[14:17]
	v_mfma_f32_16x16x32_bf16 v[10:13], v[184:187], v[232:235], v[10:13]
	s_setprio 0
	s_setprio 1
	v_mfma_f32_16x16x32_bf16 v[54:57], v[188:191], v[204:207], v[54:57]
	v_mfma_f32_16x16x32_bf16 v[50:53], v[196:199], v[204:207], v[50:53]
	v_mfma_f32_16x16x32_bf16 v[38:41], v[188:191], v[212:215], v[38:41]
	v_mfma_f32_16x16x32_bf16 v[34:37], v[196:199], v[212:215], v[34:37]
	v_mfma_f32_16x16x32_bf16 v[22:25], v[188:191], v[220:223], v[22:25]
	v_mfma_f32_16x16x32_bf16 v[18:21], v[196:199], v[220:223], v[18:21]
	v_mfma_f32_16x16x32_bf16 v[6:9], v[188:191], v[228:231], v[6:9]
	v_mfma_f32_16x16x32_bf16 v[2:5], v[196:199], v[228:231], v[2:5]
	v_mfma_f32_16x16x32_bf16 v[54:57], v[192:195], v[208:211], v[54:57]
	v_mfma_f32_16x16x32_bf16 v[50:53], v[200:203], v[208:211], v[50:53]
	v_mfma_f32_16x16x32_bf16 v[38:41], v[192:195], v[216:219], v[38:41]
	v_mfma_f32_16x16x32_bf16 v[34:37], v[200:203], v[216:219], v[34:37]
	v_mfma_f32_16x16x32_bf16 v[22:25], v[192:195], v[224:227], v[22:25]
	v_mfma_f32_16x16x32_bf16 v[18:21], v[200:203], v[224:227], v[18:21]
	v_mfma_f32_16x16x32_bf16 v[6:9], v[192:195], v[232:235], v[6:9]
	v_mfma_f32_16x16x32_bf16 v[2:5], v[200:203], v[232:235], v[2:5]
	s_setprio 0
	s_barrier
; #define PG8_STAGE(bufoff, gbase, voff) do { _Pragma("unroll") for (int _i = 0; _i < 2; ++_i) \
;         __builtin_amdgcn_global_load_lds((const unsigned*)((const char*)(gbase) + (voff)[_i]), (PG8_LAS unsigned*)(lds + (bufoff) + ldsw + _i * 8192), 16, 0, 0); } while (0)
; #define PG8_LDA(dst, b, h) do { _Pragma("unroll") for (int m = 0; m < 4; ++m) _Pragma("unroll") for (int k = 0; k < 2; ++k) dst[m][k] = *(const PG8_LAS bf16x8*)(lds + PG8_SA(b, h) + aoff + m * 2048 + k * 1024); } while (0)
; #define PG8_LDB(dst, b, h) do { _Pragma("unroll") for (int n = 0; n < 2; ++n) _Pragma("unroll") for (int k = 0; k < 2; ++k) dst[n][k] = *(const PG8_LAS bf16x8*)(lds + PG8_SB(b, h) + boff + n * 2048 + k * 1024); } while (0)
; #define PG8_MMA(ai, bj, At, Bt) do { __builtin_amdgcn_s_setprio(1); _Pragma("unroll") for (int m = 0; m < 4; ++m) _Pragma("unroll") for (int n = 0; n < 2; ++n) _Pragma("unroll") for (int k = 0; k < 2; ++k) \
;         acc[ai][bj][m][n] = __builtin_amdgcn_mfma_f32_16x16x32_bf16(Bt[n][k], At[m][k], acc[ai][bj][m][n], 0, 0, 0); __builtin_amdgcn_s_setprio(0); } while (0)
; #define PG8_WAIT_V(n) asm volatile("s_waitcnt vmcnt(" #n ")" ::: "memory")
; #define PG8_WAIT_L(n) asm volatile("s_waitcnt lgkmcnt(" #n ")" ::: "memory")
; #define PG8_BAR __builtin_amdgcn_s_barrier()
; #define PG8_SCHED __builtin_amdgcn_sched_barrier(0)
; template <class Epi, class Sched, bool ALIGN_EPI = false, bool SP2 = false, bool KSEG = false>
; __device__ __forceinline__ void gemm_phase(PG8_LAS unsigned char* lds, const Gemm g, const Sched& S, const Epi& E) {
;     ...
;             PG8_LDB(B0, 1, 0); PG8_LDB(B1, 1, 1); PG8_SCHED; PG8_LDA(At, 1, 0); PG8_STAGE(PG8_SA(0, 1), a2 + hstep, voffA);
;             PG8_WAIT_V(8); PG8_WAIT_L(0); PG8_BAR; PG8_MMA(0, 0, At, B0); PG8_MMA(0, 1, At, B1); PG8_BAR; PG8_SCHED;
	ds_read_b128 v[154:157], v250
	ds_read_b128 v[176:179], v250 offset:1024
	ds_read_b128 v[180:183], v250 offset:2048
	ds_read_b128 v[184:187], v250 offset:3072
	ds_read_b128 v[188:191], v251
	ds_read_b128 v[192:195], v251 offset:1024
	ds_read_b128 v[196:199], v251 offset:2048
	ds_read_b128 v[200:203], v251 offset:3072
	s_mov_b32 m0, s44
	v_lshl_add_u64 v[244:245], s[40:41], 0, v[140:141]
	global_load_lds_dwordx4 v[244:245], off
	s_mov_b32 m0, s45
	v_lshl_add_u64 v[244:245], s[40:41], 0, v[142:143]
	global_load_lds_dwordx4 v[244:245], off
	s_add_u32 s40, s40, 0x160000
	s_addc_u32 s41, s41, 0
	s_mov_b32 m0, s51
	v_lshl_add_u64 v[244:245], s[40:41], 0, v[140:141]
	ds_read_b128 v[204:207], v175 offset:32768
	ds_read_b128 v[208:211], v175 offset:33792
	ds_read_b128 v[212:215], v175 offset:34816
	ds_read_b128 v[216:219], v175 offset:35840
	ds_read_b128 v[220:223], v175 offset:36864
	ds_read_b128 v[224:227], v175 offset:37888
	ds_read_b128 v[228:231], v175 offset:38912
	ds_read_b128 v[232:235], v175 offset:39936
	global_load_lds_dwordx4 v[244:245], off
	s_mov_b32 m0, s52
	v_lshl_add_u64 v[244:245], s[40:41], 0, v[142:143]
	global_load_lds_dwordx4 v[244:245], off
	s_waitcnt vmcnt(8) lgkmcnt(0)
	s_barrier
	s_setprio 1
	v_mfma_f32_16x16x32_bf16 v[126:129], v[154:157], v[204:207], v[126:129]
	v_mfma_f32_16x16x32_bf16 v[122:125], v[180:183], v[204:207], v[122:125]
	v_mfma_f32_16x16x32_bf16 v[110:113], v[154:157], v[212:215], v[110:113]
	v_mfma_f32_16x16x32_bf16 v[106:109], v[180:183], v[212:215], v[106:109]
	v_mfma_f32_16x16x32_bf16 v[94:97], v[154:157], v[220:223], v[94:97]
	v_mfma_f32_16x16x32_bf16 v[90:93], v[180:183], v[220:223], v[90:93]
	v_mfma_f32_16x16x32_bf16 v[78:81], v[154:157], v[228:231], v[78:81]
	v_mfma_f32_16x16x32_bf16 v[74:77], v[180:183], v[228:231], v[74:77]
	v_mfma_f32_16x16x32_bf16 v[126:129], v[176:179], v[208:211], v[126:129]
	v_mfma_f32_16x16x32_bf16 v[122:125], v[184:187], v[208:211], v[122:125]
	v_mfma_f32_16x16x32_bf16 v[110:113], v[176:179], v[216:219], v[110:113]
	v_mfma_f32_16x16x32_bf16 v[106:109], v[184:187], v[216:219], v[106:109]
	v_mfma_f32_16x16x32_bf16 v[94:97], v[176:179], v[224:227], v[94:97]
	v_mfma_f32_16x16x32_bf16 v[90:93], v[184:187], v[224:227], v[90:93]
	v_mfma_f32_16x16x32_bf16 v[78:81], v[176:179], v[232:235], v[78:81]
	v_mfma_f32_16x16x32_bf16 v[74:77], v[184:187], v[232:235], v[74:77]
	s_setprio 0
	s_setprio 1
	v_mfma_f32_16x16x32_bf16 v[118:121], v[188:191], v[204:207], v[118:121]
	v_mfma_f32_16x16x32_bf16 v[114:117], v[196:199], v[204:207], v[114:117]
	v_mfma_f32_16x16x32_bf16 v[102:105], v[188:191], v[212:215], v[102:105]
	v_mfma_f32_16x16x32_bf16 v[98:101], v[196:199], v[212:215], v[98:101]
	v_mfma_f32_16x16x32_bf16 v[86:89], v[188:191], v[220:223], v[86:89]
	v_mfma_f32_16x16x32_bf16 v[82:85], v[196:199], v[220:223], v[82:85]
	v_mfma_f32_16x16x32_bf16 v[70:73], v[188:191], v[228:231], v[70:73]
	v_mfma_f32_16x16x32_bf16 v[66:69], v[196:199], v[228:231], v[66:69]
	v_mfma_f32_16x16x32_bf16 v[118:121], v[192:195], v[208:211], v[118:121]
	v_mfma_f32_16x16x32_bf16 v[114:117], v[200:203], v[208:211], v[114:117]
	v_mfma_f32_16x16x32_bf16 v[102:105], v[192:195], v[216:219], v[102:105]
	v_mfma_f32_16x16x32_bf16 v[98:101], v[200:203], v[216:219], v[98:101]
	v_mfma_f32_16x16x32_bf16 v[86:89], v[192:195], v[224:227], v[86:89]
	v_mfma_f32_16x16x32_bf16 v[82:85], v[200:203], v[224:227], v[82:85]
	v_mfma_f32_16x16x32_bf16 v[70:73], v[192:195], v[232:235], v[70:73]
	v_mfma_f32_16x16x32_bf16 v[66:69], v[200:203], v[232:235], v[66:69]
	s_setprio 0
	s_barrier
; #define PG8_STAGE(bufoff, gbase, voff) do { _Pragma("unroll") for (int _i = 0; _i < 2; ++_i) \
;         __builtin_amdgcn_global_load_lds((const unsigned*)((const char*)(gbase) + (voff)[_i]), (PG8_LAS unsigned*)(lds + (bufoff) + ldsw + _i * 8192), 16, 0, 0); } while (0)
; #define PG8_LDA(dst, b, h) do { _Pragma("unroll") for (int m = 0; m < 4; ++m) _Pragma("unroll") for (int k = 0; k < 2; ++k) dst[m][k] = *(const PG8_LAS bf16x8*)(lds + PG8_SA(b, h) + aoff + m * 2048 + k * 1024); } while (0)
; #define PG8_MMA(ai, bj, At, Bt) do { __builtin_amdgcn_s_setprio(1); _Pragma("unroll") for (int m = 0; m < 4; ++m) _Pragma("unroll") for (int n = 0; n < 2; ++n) _Pragma("unroll") for (int k = 0; k < 2; ++k) \
;         acc[ai][bj][m][n] = __builtin_amdgcn_mfma_f32_16x16x32_bf16(Bt[n][k], At[m][k], acc[ai][bj][m][n], 0, 0, 0); __builtin_amdgcn_s_setprio(0); } while (0)
; #define PG8_WAIT_V(n) asm volatile("s_waitcnt vmcnt(" #n ")" ::: "memory")
; #define PG8_WAIT_L(n) asm volatile("s_waitcnt lgkmcnt(" #n ")" ::: "memory")
; #define PG8_BAR __builtin_amdgcn_s_barrier()
; #define PG8_SCHED __builtin_amdgcn_sched_barrier(0)
; template <class Epi, class Sched, bool ALIGN_EPI = false, bool SP2 = false, bool KSEG = false>
; __device__ __forceinline__ void gemm_phase(PG8_LAS unsigned char* lds, const Gemm g, const Sched& S, const Epi& E) {
;     ...
;         for (int t = 0; t < nt; t += 2) {
;             const bool last = (t == nt - 2);
;             const char* a1 = cA + (size_t)(t + 1) * kstep;
;             const char* a2 = last ? nA : cA + (size_t)(t + 2) * kstep; const char* b2 = last ? nB : cB + (size_t)(t + 2) * kstep;
;             const char* a3 = a2 + kstep; const char* b3 = b2 + kstep;
;     ...
;             PG8_LDA(At, 1, 1); PG8_STAGE(PG8_SB(1, 0), b3, voffB); PG8_STAGE(PG8_SB(1, 1), b3 + hstep, voffB); PG8_STAGE(PG8_SA(1, 0), a3, voffA);
;             PG8_WAIT_V(8); PG8_WAIT_L(0); PG8_BAR; PG8_MMA(1, 0, At, B0); PG8_MMA(1, 1, At, B1); PG8_BAR; PG8_SCHED;
	v_lshl_add_u64 v[236:237], v[236:237], 0, s[26:27]
	s_add_i32 m0, s43, 0x18000
	ds_read_b128 v[204:207], v175 offset:49152
	ds_read_b128 v[208:211], v175 offset:50176
	ds_read_b128 v[212:215], v175 offset:51200
	ds_read_b128 v[216:219], v175 offset:52224
	ds_read_b128 v[220:223], v175 offset:53248
	ds_read_b128 v[224:227], v175 offset:54272
	ds_read_b128 v[228:231], v175 offset:55296
	ds_read_b128 v[232:235], v175 offset:56320
	global_load_lds_dwordx4 v[236:237], off
	s_add_i32 m0, m0, 0x2000
	s_add_u32 s38, s38, 0x160080
	v_lshl_add_u64 v[236:237], v[238:239], 0, s[26:27]
	s_addc_u32 s39, s39, 0
	global_load_lds_dwordx4 v[236:237], off
	s_add_i32 m0, s43, 0x1c000
	v_lshl_add_u64 v[236:237], s[38:39], 0, v[130:131]
	global_load_lds_dwordx4 v[236:237], off
	s_add_i32 m0, m0, 0x2000
	v_lshl_add_u64 v[236:237], s[38:39], 0, v[144:145]
	global_load_lds_dwordx4 v[236:237], off
	s_waitcnt vmcnt(6) lgkmcnt(0)
	s_barrier
	s_setprio 1
	v_mfma_f32_16x16x32_bf16 v[62:65], v[154:157], v[204:207], v[62:65]
	v_mfma_f32_16x16x32_bf16 v[58:61], v[180:183], v[204:207], v[58:61]
	v_mfma_f32_16x16x32_bf16 v[46:49], v[154:157], v[212:215], v[46:49]
	v_mfma_f32_16x16x32_bf16 v[42:45], v[180:183], v[212:215], v[42:45]
	v_mfma_f32_16x16x32_bf16 v[30:33], v[154:157], v[220:223], v[30:33]
	v_mfma_f32_16x16x32_bf16 v[26:29], v[180:183], v[220:223], v[26:29]
	v_mfma_f32_16x16x32_bf16 v[14:17], v[154:157], v[228:231], v[14:17]
	v_mfma_f32_16x16x32_bf16 v[10:13], v[180:183], v[228:231], v[10:13]
	v_mfma_f32_16x16x32_bf16 v[62:65], v[176:179], v[208:211], v[62:65]
	v_mfma_f32_16x16x32_bf16 v[58:61], v[184:187], v[208:211], v[58:61]
	v_mfma_f32_16x16x32_bf16 v[46:49], v[176:179], v[216:219], v[46:49]
	v_mfma_f32_16x16x32_bf16 v[42:45], v[184:187], v[216:219], v[42:45]
	v_mfma_f32_16x16x32_bf16 v[30:33], v[176:179], v[224:227], v[30:33]
	v_mfma_f32_16x16x32_bf16 v[26:29], v[184:187], v[224:227], v[26:29]
	v_mfma_f32_16x16x32_bf16 v[14:17], v[176:179], v[232:235], v[14:17]
	v_mfma_f32_16x16x32_bf16 v[10:13], v[184:187], v[232:235], v[10:13]
	s_setprio 0
	s_setprio 1
	v_mfma_f32_16x16x32_bf16 v[54:57], v[188:191], v[204:207], v[54:57]
	s_add_i32 s64, s64, 2
	v_mfma_f32_16x16x32_bf16 v[50:53], v[196:199], v[204:207], v[50:53]
	s_add_u32 s36, s36, 0x100
	v_mfma_f32_16x16x32_bf16 v[38:41], v[188:191], v[212:215], v[38:41]
	s_addc_u32 s37, s37, 0
	v_mfma_f32_16x16x32_bf16 v[34:37], v[196:199], v[212:215], v[34:37]
	s_add_u32 s62, s62, 0x100
	v_mfma_f32_16x16x32_bf16 v[22:25], v[188:191], v[220:223], v[22:25]
	s_addc_u32 s63, s63, 0
	v_mfma_f32_16x16x32_bf16 v[18:21], v[196:199], v[220:223], v[18:21]
	s_add_u32 s33, s36, 0xffea0080
	v_mfma_f32_16x16x32_bf16 v[6:9], v[188:191], v[228:231], v[6:9]
	s_addc_u32 s38, s37, -1
	v_mfma_f32_16x16x32_bf16 v[2:5], v[196:199], v[228:231], v[2:5]
	s_cmpk_eq_i32 s64, 0x54
	v_mfma_f32_16x16x32_bf16 v[54:57], v[192:195], v[208:211], v[54:57]
	s_cselect_b32 s41, s13, s38
	v_mfma_f32_16x16x32_bf16 v[50:53], v[200:203], v[208:211], v[50:53]
	s_cselect_b32 s40, s12, s33
	v_mfma_f32_16x16x32_bf16 v[38:41], v[192:195], v[216:219], v[38:41]
	s_cselect_b32 s39, s31, s63
	v_mfma_f32_16x16x32_bf16 v[34:37], v[200:203], v[216:219], v[34:37]
	s_cselect_b32 s38, s30, s62
	v_mfma_f32_16x16x32_bf16 v[22:25], v[192:195], v[224:227], v[22:25]
	s_add_u32 s98, s36, 0xffea0000
	v_mfma_f32_16x16x32_bf16 v[18:21], v[200:203], v[224:227], v[18:21]
	s_addc_u32 s99, s37, -1
	v_mfma_f32_16x16x32_bf16 v[6:9], v[192:195], v[232:235], v[6:9]
	s_cmpk_gt_u32 s64, 0x55
	v_mfma_f32_16x16x32_bf16 v[2:5], v[200:203], v[232:235], v[2:5]
	s_setprio 0
	s_barrier
	s_cbranch_scc0 .LBB0_537
	s_and_b64 vcc, exec, s[28:29]
	s_cbranch_vccz .LBB0_540
	s_barrier

; #define PG8_STAGE(bufoff, gbase, voff) do { _Pragma("unroll") for (int _i = 0; _i < 2; ++_i) \
;         __builtin_amdgcn_global_load_lds((const unsigned*)((const char*)(gbase) + (voff)[_i]), (PG8_LAS unsigned*)(lds + (bufoff) + ldsw + _i * 8192), 16, 0, 0); } while (0)
; #define PG8_LDA(dst, b, h) do { _Pragma("unroll") for (int m = 0; m < 4; ++m) _Pragma("unroll") for (int k = 0; k < 2; ++k) dst[m][k] = *(const PG8_LAS bf16x8*)(lds + PG8_SA(b, h) + aoff + m * 2048 + k * 1024); } while (0)
; #define PG8_LDB(dst, b, h) do { _Pragma("unroll") for (int n = 0; n < 2; ++n) _Pragma("unroll") for (int k = 0; k < 2; ++k) dst[n][k] = *(const PG8_LAS bf16x8*)(lds + PG8_SB(b, h) + boff + n * 2048 + k * 1024); } while (0)
; #define PG8_MMA(ai, bj, At, Bt) do { __builtin_amdgcn_s_setprio(1); _Pragma("unroll") for (int m = 0; m < 4; ++m) _Pragma("unroll") for (int n = 0; n < 2; ++n) _Pragma("unroll") for (int k = 0; k < 2; ++k) \
;         acc[ai][bj][m][n] = __builtin_amdgcn_mfma_f32_16x16x32_bf16(Bt[n][k], At[m][k], acc[ai][bj][m][n], 0, 0, 0); __builtin_amdgcn_s_setprio(0); } while (0)
; #define PG8_WAIT_V(n) asm volatile("s_waitcnt vmcnt(" #n ")" ::: "memory")
; #define PG8_WAIT_L(n) asm volatile("s_waitcnt lgkmcnt(" #n ")" ::: "memory")
; #define PG8_BAR __builtin_amdgcn_s_barrier()
; #define PG8_SCHED __builtin_amdgcn_sched_barrier(0)
; template <class Epi, class Sched, bool ALIGN_EPI = false, bool SP2 = false, bool KSEG = false>
; __device__ __forceinline__ void gemm_phase(PG8_LAS unsigned char* lds, const Gemm g, const Sched& S, const Epi& E) {
;     ...
;             PG8_LDB(B0, 0, 0); PG8_LDB(B1, 0, 1); PG8_SCHED; PG8_LDA(At, 0, 0); PG8_STAGE(PG8_SA(1, 1), a1 + hstep, voffA);
;             PG8_WAIT_V(8); PG8_WAIT_L(0); PG8_BAR; PG8_MMA(0, 0, At, B0); PG8_MMA(0, 1, At, B1); PG8_BAR; PG8_SCHED;
;             PG8_LDA(At, 0, 1); PG8_STAGE(PG8_SB(0, 0), b2, voffB); PG8_STAGE(PG8_SB(0, 1), b2 + hstep, voffB); PG8_STAGE(PG8_SA(0, 0), a2, voffA);
;             PG8_WAIT_V(8); PG8_WAIT_L(0); PG8_BAR; PG8_MMA(1, 0, At, B0); PG8_MMA(1, 1, At, B1); PG8_BAR; PG8_SCHED;
.LBB0_581:
	ds_read_b128 v[154:157], v160
	ds_read_b128 v[172:175], v160 offset:1024
	ds_read_b128 v[176:179], v160 offset:2048
	ds_read_b128 v[180:183], v160 offset:3072
	ds_read_b128 v[184:187], v161
	ds_read_b128 v[188:191], v161 offset:1024
	ds_read_b128 v[192:195], v161 offset:2048
	ds_read_b128 v[196:199], v161 offset:3072
	s_mov_b32 m0, s60
	v_lshl_add_u64 v[232:233], s[98:99], 0, v[132:133]
	global_load_lds_dwordx4 v[232:233], off
	s_mov_b32 m0, s61
	v_lshl_add_u64 v[232:233], s[98:99], 0, v[136:137]
	global_load_lds_dwordx4 v[232:233], off
	v_lshl_add_u64 v[232:233], s[40:41], 0, v[146:147]
	s_add_i32 m0, s55, 0xc000
	ds_read_b128 v[200:203], v164
	ds_read_b128 v[204:207], v164 offset:1024
	ds_read_b128 v[208:211], v164 offset:2048
	ds_read_b128 v[212:215], v164 offset:3072
	ds_read_b128 v[216:219], v164 offset:4096
	ds_read_b128 v[220:223], v164 offset:5120
	ds_read_b128 v[224:227], v164 offset:6144
	ds_read_b128 v[228:231], v164 offset:7168
	global_load_lds_dwordx4 v[232:233], off
	s_add_i32 m0, s55, 0xe000
	v_lshl_add_u64 v[232:233], s[40:41], 0, v[148:149]
	global_load_lds_dwordx4 v[232:233], off
	s_waitcnt vmcnt(8) lgkmcnt(0)
	s_barrier
	s_setprio 1
	v_mfma_f32_16x16x32_bf16 v[126:129], v[154:157], v[200:203], v[126:129]
	v_mfma_f32_16x16x32_bf16 v[122:125], v[176:179], v[200:203], v[122:125]
	v_mfma_f32_16x16x32_bf16 v[110:113], v[154:157], v[208:211], v[110:113]
	v_mfma_f32_16x16x32_bf16 v[106:109], v[176:179], v[208:211], v[106:109]
	v_mfma_f32_16x16x32_bf16 v[94:97], v[154:157], v[216:219], v[94:97]
	v_mfma_f32_16x16x32_bf16 v[90:93], v[176:179], v[216:219], v[90:93]
	v_mfma_f32_16x16x32_bf16 v[78:81], v[154:157], v[224:227], v[78:81]
	v_mfma_f32_16x16x32_bf16 v[74:77], v[176:179], v[224:227], v[74:77]
	v_mfma_f32_16x16x32_bf16 v[126:129], v[172:175], v[204:207], v[126:129]
	v_mfma_f32_16x16x32_bf16 v[122:125], v[180:183], v[204:207], v[122:125]
	v_mfma_f32_16x16x32_bf16 v[110:113], v[172:175], v[212:215], v[110:113]
	v_mfma_f32_16x16x32_bf16 v[106:109], v[180:183], v[212:215], v[106:109]
	v_mfma_f32_16x16x32_bf16 v[94:97], v[172:175], v[220:223], v[94:97]
	v_mfma_f32_16x16x32_bf16 v[90:93], v[180:183], v[220:223], v[90:93]
	v_mfma_f32_16x16x32_bf16 v[78:81], v[172:175], v[228:231], v[78:81]
	v_mfma_f32_16x16x32_bf16 v[74:77], v[180:183], v[228:231], v[74:77]
	s_setprio 0
	s_setprio 1
	v_mfma_f32_16x16x32_bf16 v[118:121], v[184:187], v[200:203], v[118:121]
	v_mfma_f32_16x16x32_bf16 v[114:117], v[192:195], v[200:203], v[114:117]
	v_mfma_f32_16x16x32_bf16 v[102:105], v[184:187], v[208:211], v[102:105]
	v_mfma_f32_16x16x32_bf16 v[98:101], v[192:195], v[208:211], v[98:101]
	v_mfma_f32_16x16x32_bf16 v[86:89], v[184:187], v[216:219], v[86:89]
	v_mfma_f32_16x16x32_bf16 v[82:85], v[192:195], v[216:219], v[82:85]
	v_mfma_f32_16x16x32_bf16 v[70:73], v[184:187], v[224:227], v[70:73]
	v_mfma_f32_16x16x32_bf16 v[66:69], v[192:195], v[224:227], v[66:69]
	v_mfma_f32_16x16x32_bf16 v[118:121], v[188:191], v[204:207], v[118:121]
	v_mfma_f32_16x16x32_bf16 v[114:117], v[196:199], v[204:207], v[114:117]
	v_mfma_f32_16x16x32_bf16 v[102:105], v[188:191], v[212:215], v[102:105]
	v_mfma_f32_16x16x32_bf16 v[98:101], v[196:199], v[212:215], v[98:101]
	v_mfma_f32_16x16x32_bf16 v[86:89], v[188:191], v[220:223], v[86:89]
	v_mfma_f32_16x16x32_bf16 v[82:85], v[196:199], v[220:223], v[82:85]
	v_mfma_f32_16x16x32_bf16 v[70:73], v[188:191], v[228:231], v[70:73]
	v_mfma_f32_16x16x32_bf16 v[66:69], v[196:199], v[228:231], v[66:69]
	s_setprio 0
	s_barrier
	v_lshl_add_u64 v[232:233], s[42:43], 0, v[134:135]
	s_add_i32 m0, s62, s53
	ds_read_b128 v[200:203], v164 offset:16384
	ds_read_b128 v[204:207], v164 offset:17408
	ds_read_b128 v[208:211], v164 offset:18432
	ds_read_b128 v[212:215], v164 offset:19456
	ds_read_b128 v[216:219], v164 offset:20480
	ds_read_b128 v[220:223], v164 offset:21504
	ds_read_b128 v[224:227], v164 offset:22528
	ds_read_b128 v[228:231], v164 offset:23552
	global_load_lds_dwordx4 v[232:233], off
	s_add_i32 m0, m0, 0x2000
	s_add_u32 s80, s42, 0x80000
	v_lshl_add_u64 v[234:235], s[42:43], 0, v[138:139]
	s_addc_u32 s81, s43, 0
	global_load_lds_dwordx4 v[234:235], off
	s_add_i32 m0, s63, s53
	v_lshl_add_u64 v[236:237], s[80:81], 0, v[134:135]
	global_load_lds_dwordx4 v[236:237], off
	s_add_i32 m0, m0, 0x2000
	v_lshl_add_u64 v[236:237], s[80:81], 0, v[138:139]
	global_load_lds_dwordx4 v[236:237], off
	s_waitcnt vmcnt(6) lgkmcnt(0)
	s_barrier
	s_setprio 1
	v_mfma_f32_16x16x32_bf16 v[62:65], v[154:157], v[200:203], v[62:65]
	v_mfma_f32_16x16x32_bf16 v[58:61], v[176:179], v[200:203], v[58:61]
	v_mfma_f32_16x16x32_bf16 v[46:49], v[154:157], v[208:211], v[46:49]
	v_mfma_f32_16x16x32_bf16 v[42:45], v[176:179], v[208:211], v[42:45]
	v_mfma_f32_16x16x32_bf16 v[30:33], v[154:157], v[216:219], v[30:33]
	v_mfma_f32_16x16x32_bf16 v[26:29], v[176:179], v[216:219], v[26:29]
	v_mfma_f32_16x16x32_bf16 v[14:17], v[154:157], v[224:227], v[14:17]
	v_mfma_f32_16x16x32_bf16 v[10:13], v[176:179], v[224:227], v[10:13]
	v_mfma_f32_16x16x32_bf16 v[62:65], v[172:175], v[204:207], v[62:65]
	v_mfma_f32_16x16x32_bf16 v[58:61], v[180:183], v[204:207], v[58:61]
	v_mfma_f32_16x16x32_bf16 v[46:49], v[172:175], v[212:215], v[46:49]
	v_mfma_f32_16x16x32_bf16 v[42:45], v[180:183], v[212:215], v[42:45]
	v_mfma_f32_16x16x32_bf16 v[30:33], v[172:175], v[220:223], v[30:33]
	v_mfma_f32_16x16x32_bf16 v[26:29], v[180:183], v[220:223], v[26:29]
	v_mfma_f32_16x16x32_bf16 v[14:17], v[172:175], v[228:231], v[14:17]
	v_mfma_f32_16x16x32_bf16 v[10:13], v[180:183], v[228:231], v[10:13]
	s_setprio 0
	s_setprio 1
	v_mfma_f32_16x16x32_bf16 v[54:57], v[184:187], v[200:203], v[54:57]
	v_mfma_f32_16x16x32_bf16 v[50:53], v[192:195], v[200:203], v[50:53]
	v_mfma_f32_16x16x32_bf16 v[38:41], v[184:187], v[208:211], v[38:41]
	v_mfma_f32_16x16x32_bf16 v[34:37], v[192:195], v[208:211], v[34:37]
	v_mfma_f32_16x16x32_bf16 v[22:25], v[184:187], v[216:219], v[22:25]
	v_mfma_f32_16x16x32_bf16 v[18:21], v[192:195], v[216:219], v[18:21]
	v_mfma_f32_16x16x32_bf16 v[6:9], v[184:187], v[224:227], v[6:9]
	v_mfma_f32_16x16x32_bf16 v[2:5], v[192:195], v[224:227], v[2:5]
	v_mfma_f32_16x16x32_bf16 v[54:57], v[188:191], v[204:207], v[54:57]
	v_mfma_f32_16x16x32_bf16 v[50:53], v[196:199], v[204:207], v[50:53]
	v_mfma_f32_16x16x32_bf16 v[38:41], v[188:191], v[212:215], v[38:41]
	v_mfma_f32_16x16x32_bf16 v[34:37], v[196:199], v[212:215], v[34:37]
	v_mfma_f32_16x16x32_bf16 v[22:25], v[188:191], v[220:223], v[22:25]
	v_mfma_f32_16x16x32_bf16 v[18:21], v[196:199], v[220:223], v[18:21]
	v_mfma_f32_16x16x32_bf16 v[6:9], v[188:191], v[228:231], v[6:9]
	v_mfma_f32_16x16x32_bf16 v[2:5], v[196:199], v[228:231], v[2:5]
	s_setprio 0
	s_barrier
; #define PG8_STAGE(bufoff, gbase, voff) do { _Pragma("unroll") for (int _i = 0; _i < 2; ++_i) \
;         __builtin_amdgcn_global_load_lds((const unsigned*)((const char*)(gbase) + (voff)[_i]), (PG8_LAS unsigned*)(lds + (bufoff) + ldsw + _i * 8192), 16, 0, 0); } while (0)
; #define PG8_LDA(dst, b, h) do { _Pragma("unroll") for (int m = 0; m < 4; ++m) _Pragma("unroll") for (int k = 0; k < 2; ++k) dst[m][k] = *(const PG8_LAS bf16x8*)(lds + PG8_SA(b, h) + aoff + m * 2048 + k * 1024); } while (0)
; #define PG8_LDB(dst, b, h) do { _Pragma("unroll") for (int n = 0; n < 2; ++n) _Pragma("unroll") for (int k = 0; k < 2; ++k) dst[n][k] = *(const PG8_LAS bf16x8*)(lds + PG8_SB(b, h) + boff + n * 2048 + k * 1024); } while (0)
; #define PG8_MMA(ai, bj, At, Bt) do { __builtin_amdgcn_s_setprio(1); _Pragma("unroll") for (int m = 0; m < 4; ++m) _Pragma("unroll") for (int n = 0; n < 2; ++n) _Pragma("unroll") for (int k = 0; k < 2; ++k) \
;         acc[ai][bj][m][n] = __builtin_amdgcn_mfma_f32_16x16x32_bf16(Bt[n][k], At[m][k], acc[ai][bj][m][n], 0, 0, 0); __builtin_amdgcn_s_setprio(0); } while (0)
; #define PG8_WAIT_V(n) asm volatile("s_waitcnt vmcnt(" #n ")" ::: "memory")
; #define PG8_WAIT_L(n) asm volatile("s_waitcnt lgkmcnt(" #n ")" ::: "memory")
; #define PG8_BAR __builtin_amdgcn_s_barrier()
; #define PG8_SCHED __builtin_amdgcn_sched_barrier(0)
; template <class Epi, class Sched, bool ALIGN_EPI = false, bool SP2 = false, bool KSEG = false>
; __device__ __forceinline__ void gemm_phase(PG8_LAS unsigned char* lds, const Gemm g, const Sched& S, const Epi& E) {
;     ...
;             PG8_LDB(B0, 1, 0); PG8_LDB(B1, 1, 1); PG8_SCHED; PG8_LDA(At, 1, 0); PG8_STAGE(PG8_SA(0, 1), a2 + hstep, voffA);
;             PG8_WAIT_V(8); PG8_WAIT_L(0); PG8_BAR; PG8_MMA(0, 0, At, B0); PG8_MMA(0, 1, At, B1); PG8_BAR; PG8_SCHED;
	ds_read_b128 v[154:157], v250
	ds_read_b128 v[172:175], v250 offset:1024
	ds_read_b128 v[176:179], v250 offset:2048
	ds_read_b128 v[180:183], v250 offset:3072
	ds_read_b128 v[184:187], v251
	ds_read_b128 v[188:191], v251 offset:1024
	ds_read_b128 v[192:195], v251 offset:2048
	ds_read_b128 v[196:199], v251 offset:3072
	s_mov_b32 m0, s55
	v_lshl_add_u64 v[240:241], s[44:45], 0, v[132:133]
	global_load_lds_dwordx4 v[240:241], off
	s_mov_b32 m0, s56
	v_lshl_add_u64 v[240:241], s[44:45], 0, v[136:137]
	global_load_lds_dwordx4 v[240:241], off
	s_add_u32 s44, s44, 0x80000
	s_addc_u32 s45, s45, 0
	s_mov_b32 m0, s57
	v_lshl_add_u64 v[240:241], s[44:45], 0, v[132:133]
	ds_read_b128 v[200:203], v164 offset:32768
	ds_read_b128 v[204:207], v164 offset:33792
	ds_read_b128 v[208:211], v164 offset:34816
	ds_read_b128 v[212:215], v164 offset:35840
	ds_read_b128 v[216:219], v164 offset:36864
	ds_read_b128 v[220:223], v164 offset:37888
	ds_read_b128 v[224:227], v164 offset:38912
	ds_read_b128 v[228:231], v164 offset:39936
	global_load_lds_dwordx4 v[240:241], off
	s_mov_b32 m0, s58
	v_lshl_add_u64 v[240:241], s[44:45], 0, v[136:137]
	global_load_lds_dwordx4 v[240:241], off
	s_waitcnt vmcnt(8) lgkmcnt(0)
	s_barrier
	s_setprio 1
	v_mfma_f32_16x16x32_bf16 v[126:129], v[154:157], v[200:203], v[126:129]
	v_mfma_f32_16x16x32_bf16 v[122:125], v[176:179], v[200:203], v[122:125]
	v_mfma_f32_16x16x32_bf16 v[110:113], v[154:157], v[208:211], v[110:113]
	v_mfma_f32_16x16x32_bf16 v[106:109], v[176:179], v[208:211], v[106:109]
	v_mfma_f32_16x16x32_bf16 v[94:97], v[154:157], v[216:219], v[94:97]
	v_mfma_f32_16x16x32_bf16 v[90:93], v[176:179], v[216:219], v[90:93]
	v_mfma_f32_16x16x32_bf16 v[78:81], v[154:157], v[224:227], v[78:81]
	v_mfma_f32_16x16x32_bf16 v[74:77], v[176:179], v[224:227], v[74:77]
	v_mfma_f32_16x16x32_bf16 v[126:129], v[172:175], v[204:207], v[126:129]
	v_mfma_f32_16x16x32_bf16 v[122:125], v[180:183], v[204:207], v[122:125]
	v_mfma_f32_16x16x32_bf16 v[110:113], v[172:175], v[212:215], v[110:113]
	v_mfma_f32_16x16x32_bf16 v[106:109], v[180:183], v[212:215], v[106:109]
	v_mfma_f32_16x16x32_bf16 v[94:97], v[172:175], v[220:223], v[94:97]
	v_mfma_f32_16x16x32_bf16 v[90:93], v[180:183], v[220:223], v[90:93]
	v_mfma_f32_16x16x32_bf16 v[78:81], v[172:175], v[228:231], v[78:81]
	v_mfma_f32_16x16x32_bf16 v[74:77], v[180:183], v[228:231], v[74:77]
	s_setprio 0
	s_setprio 1
	v_mfma_f32_16x16x32_bf16 v[118:121], v[184:187], v[200:203], v[118:121]
	v_mfma_f32_16x16x32_bf16 v[114:117], v[192:195], v[200:203], v[114:117]
	v_mfma_f32_16x16x32_bf16 v[102:105], v[184:187], v[208:211], v[102:105]
	v_mfma_f32_16x16x32_bf16 v[98:101], v[192:195], v[208:211], v[98:101]
	v_mfma_f32_16x16x32_bf16 v[86:89], v[184:187], v[216:219], v[86:89]
	v_mfma_f32_16x16x32_bf16 v[82:85], v[192:195], v[216:219], v[82:85]
	v_mfma_f32_16x16x32_bf16 v[70:73], v[184:187], v[224:227], v[70:73]
	v_mfma_f32_16x16x32_bf16 v[66:69], v[192:195], v[224:227], v[66:69]
	v_mfma_f32_16x16x32_bf16 v[118:121], v[188:191], v[204:207], v[118:121]
	v_mfma_f32_16x16x32_bf16 v[114:117], v[196:199], v[204:207], v[114:117]
	v_mfma_f32_16x16x32_bf16 v[102:105], v[188:191], v[212:215], v[102:105]
	v_mfma_f32_16x16x32_bf16 v[98:101], v[196:199], v[212:215], v[98:101]
	v_mfma_f32_16x16x32_bf16 v[86:89], v[188:191], v[220:223], v[86:89]
	v_mfma_f32_16x16x32_bf16 v[82:85], v[196:199], v[220:223], v[82:85]
	v_mfma_f32_16x16x32_bf16 v[70:73], v[188:191], v[228:231], v[70:73]
	v_mfma_f32_16x16x32_bf16 v[66:69], v[196:199], v[228:231], v[66:69]
	s_setprio 0
	s_barrier
; #define PG8_STAGE(bufoff, gbase, voff) do { _Pragma("unroll") for (int _i = 0; _i < 2; ++_i) \
;         __builtin_amdgcn_global_load_lds((const unsigned*)((const char*)(gbase) + (voff)[_i]), (PG8_LAS unsigned*)(lds + (bufoff) + ldsw + _i * 8192), 16, 0, 0); } while (0)
; #define PG8_LDA(dst, b, h) do { _Pragma("unroll") for (int m = 0; m < 4; ++m) _Pragma("unroll") for (int k = 0; k < 2; ++k) dst[m][k] = *(const PG8_LAS bf16x8*)(lds + PG8_SA(b, h) + aoff + m * 2048 + k * 1024); } while (0)
; #define PG8_MMA(ai, bj, At, Bt) do { __builtin_amdgcn_s_setprio(1); _Pragma("unroll") for (int m = 0; m < 4; ++m) _Pragma("unroll") for (int n = 0; n < 2; ++n) _Pragma("unroll") for (int k = 0; k < 2; ++k) \
;         acc[ai][bj][m][n] = __builtin_amdgcn_mfma_f32_16x16x32_bf16(Bt[n][k], At[m][k], acc[ai][bj][m][n], 0, 0, 0); __builtin_amdgcn_s_setprio(0); } while (0)
; #define PG8_WAIT_V(n) asm volatile("s_waitcnt vmcnt(" #n ")" ::: "memory")
; #define PG8_WAIT_L(n) asm volatile("s_waitcnt lgkmcnt(" #n ")" ::: "memory")
; #define PG8_BAR __builtin_amdgcn_s_barrier()
; #define PG8_SCHED __builtin_amdgcn_sched_barrier(0)
; template <class Epi, class Sched, bool ALIGN_EPI = false, bool SP2 = false, bool KSEG = false>
; __device__ __forceinline__ void gemm_phase(PG8_LAS unsigned char* lds, const Gemm g, const Sched& S, const Epi& E) {
;     ...
;         for (int t = 0; t < nt; t += 2) {
;             const bool last = (t == nt - 2);
;             const char* a1 = cA + (size_t)(t + 1) * kstep;
;             const char* a2 = last ? nA : cA + (size_t)(t + 2) * kstep; const char* b2 = last ? nB : cB + (size_t)(t + 2) * kstep;
;             const char* a3 = a2 + kstep; const char* b3 = b2 + kstep;
;     ...
;             PG8_LDA(At, 1, 1); PG8_STAGE(PG8_SB(1, 0), b3, voffB); PG8_STAGE(PG8_SB(1, 1), b3 + hstep, voffB); PG8_STAGE(PG8_SA(1, 0), a3, voffA);
;             PG8_WAIT_V(8); PG8_WAIT_L(0); PG8_BAR; PG8_MMA(1, 0, At, B0); PG8_MMA(1, 1, At, B1); PG8_BAR; PG8_SCHED;
	v_lshl_add_u64 v[232:233], v[232:233], 0, s[12:13]
	s_add_i32 m0, s53, 0x18000
	ds_read_b128 v[200:203], v164 offset:49152
	ds_read_b128 v[204:207], v164 offset:50176
	ds_read_b128 v[208:211], v164 offset:51200
	ds_read_b128 v[212:215], v164 offset:52224
	ds_read_b128 v[216:219], v164 offset:53248
	ds_read_b128 v[220:223], v164 offset:54272
	ds_read_b128 v[224:227], v164 offset:55296
	ds_read_b128 v[228:231], v164 offset:56320
	global_load_lds_dwordx4 v[232:233], off
	s_add_i32 m0, m0, 0x2000
	s_add_u32 s42, s42, 0x80080
	v_lshl_add_u64 v[232:233], v[234:235], 0, s[12:13]
	s_addc_u32 s43, s43, 0
	global_load_lds_dwordx4 v[232:233], off
	s_add_i32 m0, s53, 0x1c000
	v_lshl_add_u64 v[232:233], s[42:43], 0, v[134:135]
	global_load_lds_dwordx4 v[232:233], off
	s_add_i32 m0, m0, 0x2000
	v_lshl_add_u64 v[232:233], s[42:43], 0, v[138:139]
	global_load_lds_dwordx4 v[232:233], off
	s_waitcnt vmcnt(6) lgkmcnt(0)
	s_barrier
	s_setprio 1
	v_mfma_f32_16x16x32_bf16 v[62:65], v[154:157], v[200:203], v[62:65]
	v_mfma_f32_16x16x32_bf16 v[58:61], v[176:179], v[200:203], v[58:61]
	v_mfma_f32_16x16x32_bf16 v[46:49], v[154:157], v[208:211], v[46:49]
	v_mfma_f32_16x16x32_bf16 v[42:45], v[176:179], v[208:211], v[42:45]
	v_mfma_f32_16x16x32_bf16 v[30:33], v[154:157], v[216:219], v[30:33]
	v_mfma_f32_16x16x32_bf16 v[26:29], v[176:179], v[216:219], v[26:29]
	v_mfma_f32_16x16x32_bf16 v[14:17], v[154:157], v[224:227], v[14:17]
	v_mfma_f32_16x16x32_bf16 v[10:13], v[176:179], v[224:227], v[10:13]
	v_mfma_f32_16x16x32_bf16 v[62:65], v[172:175], v[204:207], v[62:65]
	v_mfma_f32_16x16x32_bf16 v[58:61], v[180:183], v[204:207], v[58:61]
	v_mfma_f32_16x16x32_bf16 v[46:49], v[172:175], v[212:215], v[46:49]
	v_mfma_f32_16x16x32_bf16 v[42:45], v[180:183], v[212:215], v[42:45]
	v_mfma_f32_16x16x32_bf16 v[30:33], v[172:175], v[220:223], v[30:33]
	v_mfma_f32_16x16x32_bf16 v[26:29], v[180:183], v[220:223], v[26:29]
	v_mfma_f32_16x16x32_bf16 v[14:17], v[172:175], v[228:231], v[14:17]
	v_mfma_f32_16x16x32_bf16 v[10:13], v[180:183], v[228:231], v[10:13]
	s_setprio 0
	s_setprio 1
	v_mfma_f32_16x16x32_bf16 v[54:57], v[184:187], v[200:203], v[54:57]
	s_add_i32 s79, s79, 2
	v_mfma_f32_16x16x32_bf16 v[50:53], v[192:195], v[200:203], v[50:53]
	s_add_u32 s40, s40, 0x100
	v_mfma_f32_16x16x32_bf16 v[38:41], v[184:187], v[208:211], v[38:41]
	s_addc_u32 s41, s41, 0
	v_mfma_f32_16x16x32_bf16 v[34:37], v[192:195], v[208:211], v[34:37]
	s_add_u32 s67, s67, 0x100
	v_mfma_f32_16x16x32_bf16 v[22:25], v[184:187], v[216:219], v[22:25]
	s_addc_u32 s78, s78, 0
	v_mfma_f32_16x16x32_bf16 v[18:21], v[192:195], v[216:219], v[18:21]
	s_add_u32 s33, s40, 0xfff80080
	v_mfma_f32_16x16x32_bf16 v[6:9], v[184:187], v[224:227], v[6:9]
	s_addc_u32 s42, s41, -1
	v_mfma_f32_16x16x32_bf16 v[2:5], v[192:195], v[224:227], v[2:5]
	s_cmp_eq_u32 s79, 28
	v_mfma_f32_16x16x32_bf16 v[54:57], v[188:191], v[204:207], v[54:57]
	s_cselect_b32 s45, s29, s42
	v_mfma_f32_16x16x32_bf16 v[50:53], v[196:199], v[204:207], v[50:53]
	s_cselect_b32 s44, s65, s33
	v_mfma_f32_16x16x32_bf16 v[38:41], v[188:191], v[212:215], v[38:41]
	s_cselect_b32 s43, s27, s78
	v_mfma_f32_16x16x32_bf16 v[34:37], v[196:199], v[212:215], v[34:37]
	s_cselect_b32 s42, s66, s67
	v_mfma_f32_16x16x32_bf16 v[22:25], v[188:191], v[220:223], v[22:25]
	s_add_u32 s98, s40, 0xfff80000
	v_mfma_f32_16x16x32_bf16 v[18:21], v[196:199], v[220:223], v[18:21]
	s_addc_u32 s99, s41, -1
	v_mfma_f32_16x16x32_bf16 v[6:9], v[188:191], v[228:231], v[6:9]
	s_cmp_lt_u32 s79, 30
	v_mfma_f32_16x16x32_bf16 v[2:5], v[196:199], v[228:231], v[2:5]
	s_setprio 0
	s_barrier
	s_cbranch_scc1 .LBB0_581
	s_andn2_b64 vcc, exec, s[24:25]
	s_cbranch_vccnz .LBB0_584
	s_barrier

; #define PG8_STAGE(bufoff, gbase, voff) do { _Pragma("unroll") for (int _i = 0; _i < 2; ++_i) \
;         __builtin_amdgcn_global_load_lds((const unsigned*)((const char*)(gbase) + (voff)[_i]), (PG8_LAS unsigned*)(lds + (bufoff) + ldsw + _i * 8192), 16, 0, 0); } while (0)
; #define PG8_LDA(dst, b, h) do { _Pragma("unroll") for (int m = 0; m < 4; ++m) _Pragma("unroll") for (int k = 0; k < 2; ++k) dst[m][k] = *(const PG8_LAS bf16x8*)(lds + PG8_SA(b, h) + aoff + m * 2048 + k * 1024); } while (0)
; #define PG8_LDB(dst, b, h) do { _Pragma("unroll") for (int n = 0; n < 2; ++n) _Pragma("unroll") for (int k = 0; k < 2; ++k) dst[n][k] = *(const PG8_LAS bf16x8*)(lds + PG8_SB(b, h) + boff + n * 2048 + k * 1024); } while (0)
; #define PG8_MMA(ai, bj, At, Bt) do { __builtin_amdgcn_s_setprio(1); _Pragma("unroll") for (int m = 0; m < 4; ++m) _Pragma("unroll") for (int n = 0; n < 2; ++n) _Pragma("unroll") for (int k = 0; k < 2; ++k) \
;         acc[ai][bj][m][n] = __builtin_amdgcn_mfma_f32_16x16x32_bf16(Bt[n][k], At[m][k], acc[ai][bj][m][n], 0, 0, 0); __builtin_amdgcn_s_setprio(0); } while (0)
; #define PG8_WAIT_V(n) asm volatile("s_waitcnt vmcnt(" #n ")" ::: "memory")
; #define PG8_WAIT_L(n) asm volatile("s_waitcnt lgkmcnt(" #n ")" ::: "memory")
; #define PG8_BAR __builtin_amdgcn_s_barrier()
; #define PG8_SCHED __builtin_amdgcn_sched_barrier(0)
; template <class Epi, class Sched, bool ALIGN_EPI = false, bool SP2 = false, bool KSEG = false>
; __device__ __forceinline__ void gemm_phase(PG8_LAS unsigned char* lds, const Gemm g, const Sched& S, const Epi& E) {
;     ...
;             PG8_LDB(B0, 0, 0); PG8_LDB(B1, 0, 1); PG8_SCHED; PG8_LDA(At, 0, 0); PG8_STAGE(PG8_SA(1, 1), a1 + hstep, voffA);
;             PG8_WAIT_V(8); PG8_WAIT_L(0); PG8_BAR; PG8_MMA(0, 0, At, B0); PG8_MMA(0, 1, At, B1); PG8_BAR; PG8_SCHED;
;             PG8_LDA(At, 0, 1); PG8_STAGE(PG8_SB(0, 0), b2, voffB); PG8_STAGE(PG8_SB(0, 1), b2 + hstep, voffB); PG8_STAGE(PG8_SA(0, 0), a2, voffA);
;             PG8_WAIT_V(8); PG8_WAIT_L(0); PG8_BAR; PG8_MMA(1, 0, At, B0); PG8_MMA(1, 1, At, B1); PG8_BAR; PG8_SCHED;
.LBB0_621:
	ds_read_b128 v[146:149], v1
	ds_read_b128 v[156:159], v1 offset:1024
	ds_read_b128 v[160:163], v1 offset:2048
	ds_read_b128 v[164:167], v1 offset:3072
	ds_read_b128 v[168:171], v153
	ds_read_b128 v[172:175], v153 offset:1024
	ds_read_b128 v[176:179], v153 offset:2048
	ds_read_b128 v[180:183], v153 offset:3072
	s_mov_b32 m0, s40
	v_lshl_add_u64 v[216:217], s[98:99], 0, v[140:141]
	global_load_lds_dwordx4 v[216:217], off
	s_mov_b32 m0, s41
	v_lshl_add_u64 v[216:217], s[98:99], 0, v[142:143]
	global_load_lds_dwordx4 v[216:217], off
	v_lshl_add_u64 v[216:217], s[24:25], 0, v[132:133]
	s_add_i32 m0, s31, 0xc000
	ds_read_b128 v[184:187], v154
	ds_read_b128 v[188:191], v154 offset:1024
	ds_read_b128 v[192:195], v154 offset:2048
	ds_read_b128 v[196:199], v154 offset:3072
	ds_read_b128 v[200:203], v154 offset:4096
	ds_read_b128 v[204:207], v154 offset:5120
	ds_read_b128 v[208:211], v154 offset:6144
	ds_read_b128 v[212:215], v154 offset:7168
	global_load_lds_dwordx4 v[216:217], off
	s_add_i32 m0, s31, 0xe000
	v_lshl_add_u64 v[216:217], s[24:25], 0, v[134:135]
	global_load_lds_dwordx4 v[216:217], off
	s_waitcnt vmcnt(8) lgkmcnt(0)
	s_barrier
	s_setprio 1
	v_mfma_f32_16x16x32_bf16 v[126:129], v[146:149], v[184:187], v[126:129]
	v_mfma_f32_16x16x32_bf16 v[122:125], v[160:163], v[184:187], v[122:125]
	v_mfma_f32_16x16x32_bf16 v[110:113], v[146:149], v[192:195], v[110:113]
	v_mfma_f32_16x16x32_bf16 v[106:109], v[160:163], v[192:195], v[106:109]
	v_mfma_f32_16x16x32_bf16 v[94:97], v[146:149], v[200:203], v[94:97]
	v_mfma_f32_16x16x32_bf16 v[90:93], v[160:163], v[200:203], v[90:93]
	v_mfma_f32_16x16x32_bf16 v[78:81], v[146:149], v[208:211], v[78:81]
	v_mfma_f32_16x16x32_bf16 v[74:77], v[160:163], v[208:211], v[74:77]
	v_mfma_f32_16x16x32_bf16 v[126:129], v[156:159], v[188:191], v[126:129]
	v_mfma_f32_16x16x32_bf16 v[122:125], v[164:167], v[188:191], v[122:125]
	v_mfma_f32_16x16x32_bf16 v[110:113], v[156:159], v[196:199], v[110:113]
	v_mfma_f32_16x16x32_bf16 v[106:109], v[164:167], v[196:199], v[106:109]
	v_mfma_f32_16x16x32_bf16 v[94:97], v[156:159], v[204:207], v[94:97]
	v_mfma_f32_16x16x32_bf16 v[90:93], v[164:167], v[204:207], v[90:93]
	v_mfma_f32_16x16x32_bf16 v[78:81], v[156:159], v[212:215], v[78:81]
	v_mfma_f32_16x16x32_bf16 v[74:77], v[164:167], v[212:215], v[74:77]
	s_setprio 0
	s_setprio 1
	v_mfma_f32_16x16x32_bf16 v[118:121], v[168:171], v[184:187], v[118:121]
	v_mfma_f32_16x16x32_bf16 v[114:117], v[176:179], v[184:187], v[114:117]
	v_mfma_f32_16x16x32_bf16 v[102:105], v[168:171], v[192:195], v[102:105]
	v_mfma_f32_16x16x32_bf16 v[98:101], v[176:179], v[192:195], v[98:101]
	v_mfma_f32_16x16x32_bf16 v[86:89], v[168:171], v[200:203], v[86:89]
	v_mfma_f32_16x16x32_bf16 v[82:85], v[176:179], v[200:203], v[82:85]
	v_mfma_f32_16x16x32_bf16 v[70:73], v[168:171], v[208:211], v[70:73]
	v_mfma_f32_16x16x32_bf16 v[66:69], v[176:179], v[208:211], v[66:69]
	v_mfma_f32_16x16x32_bf16 v[118:121], v[172:175], v[188:191], v[118:121]
	v_mfma_f32_16x16x32_bf16 v[114:117], v[180:183], v[188:191], v[114:117]
	v_mfma_f32_16x16x32_bf16 v[102:105], v[172:175], v[196:199], v[102:105]
	v_mfma_f32_16x16x32_bf16 v[98:101], v[180:183], v[196:199], v[98:101]
	v_mfma_f32_16x16x32_bf16 v[86:89], v[172:175], v[204:207], v[86:89]
	v_mfma_f32_16x16x32_bf16 v[82:85], v[180:183], v[204:207], v[82:85]
	v_mfma_f32_16x16x32_bf16 v[70:73], v[172:175], v[212:215], v[70:73]
	v_mfma_f32_16x16x32_bf16 v[66:69], v[180:183], v[212:215], v[66:69]
	s_setprio 0
	s_barrier
	v_lshl_add_u64 v[216:217], s[26:27], 0, v[130:131]
	s_add_i32 m0, s42, s30
	ds_read_b128 v[184:187], v154 offset:16384
	ds_read_b128 v[188:191], v154 offset:17408
	ds_read_b128 v[192:195], v154 offset:18432
	ds_read_b128 v[196:199], v154 offset:19456
	ds_read_b128 v[200:203], v154 offset:20480
	ds_read_b128 v[204:207], v154 offset:21504
	ds_read_b128 v[208:211], v154 offset:22528
	ds_read_b128 v[212:215], v154 offset:23552
	global_load_lds_dwordx4 v[216:217], off
	s_add_i32 m0, m0, 0x2000
	s_add_u32 s54, s26, 0x160000
	v_lshl_add_u64 v[218:219], s[26:27], 0, v[144:145]
	s_addc_u32 s55, s27, 0
	global_load_lds_dwordx4 v[218:219], off
	s_add_i32 m0, s43, s30
	v_lshl_add_u64 v[220:221], s[54:55], 0, v[130:131]
	global_load_lds_dwordx4 v[220:221], off
	s_add_i32 m0, m0, 0x2000
	v_lshl_add_u64 v[220:221], s[54:55], 0, v[144:145]
	global_load_lds_dwordx4 v[220:221], off
	s_waitcnt vmcnt(6) lgkmcnt(0)
	s_barrier
	s_setprio 1
	v_mfma_f32_16x16x32_bf16 v[62:65], v[146:149], v[184:187], v[62:65]
	v_mfma_f32_16x16x32_bf16 v[58:61], v[160:163], v[184:187], v[58:61]
	v_mfma_f32_16x16x32_bf16 v[46:49], v[146:149], v[192:195], v[46:49]
	v_mfma_f32_16x16x32_bf16 v[42:45], v[160:163], v[192:195], v[42:45]
	v_mfma_f32_16x16x32_bf16 v[30:33], v[146:149], v[200:203], v[30:33]
	v_mfma_f32_16x16x32_bf16 v[26:29], v[160:163], v[200:203], v[26:29]
	v_mfma_f32_16x16x32_bf16 v[14:17], v[146:149], v[208:211], v[14:17]
	v_mfma_f32_16x16x32_bf16 v[10:13], v[160:163], v[208:211], v[10:13]
	v_mfma_f32_16x16x32_bf16 v[62:65], v[156:159], v[188:191], v[62:65]
	v_mfma_f32_16x16x32_bf16 v[58:61], v[164:167], v[188:191], v[58:61]
	v_mfma_f32_16x16x32_bf16 v[46:49], v[156:159], v[196:199], v[46:49]
	v_mfma_f32_16x16x32_bf16 v[42:45], v[164:167], v[196:199], v[42:45]
	v_mfma_f32_16x16x32_bf16 v[30:33], v[156:159], v[204:207], v[30:33]
	v_mfma_f32_16x16x32_bf16 v[26:29], v[164:167], v[204:207], v[26:29]
	v_mfma_f32_16x16x32_bf16 v[14:17], v[156:159], v[212:215], v[14:17]
	v_mfma_f32_16x16x32_bf16 v[10:13], v[164:167], v[212:215], v[10:13]
	s_setprio 0
	s_setprio 1
	v_mfma_f32_16x16x32_bf16 v[54:57], v[168:171], v[184:187], v[54:57]
	v_mfma_f32_16x16x32_bf16 v[50:53], v[176:179], v[184:187], v[50:53]
	v_mfma_f32_16x16x32_bf16 v[38:41], v[168:171], v[192:195], v[38:41]
	v_mfma_f32_16x16x32_bf16 v[34:37], v[176:179], v[192:195], v[34:37]
	v_mfma_f32_16x16x32_bf16 v[22:25], v[168:171], v[200:203], v[22:25]
	v_mfma_f32_16x16x32_bf16 v[18:21], v[176:179], v[200:203], v[18:21]
	v_mfma_f32_16x16x32_bf16 v[6:9], v[168:171], v[208:211], v[6:9]
	v_mfma_f32_16x16x32_bf16 v[2:5], v[176:179], v[208:211], v[2:5]
	v_mfma_f32_16x16x32_bf16 v[54:57], v[172:175], v[188:191], v[54:57]
	v_mfma_f32_16x16x32_bf16 v[50:53], v[180:183], v[188:191], v[50:53]
	v_mfma_f32_16x16x32_bf16 v[38:41], v[172:175], v[196:199], v[38:41]
	v_mfma_f32_16x16x32_bf16 v[34:37], v[180:183], v[196:199], v[34:37]
	v_mfma_f32_16x16x32_bf16 v[22:25], v[172:175], v[204:207], v[22:25]
	v_mfma_f32_16x16x32_bf16 v[18:21], v[180:183], v[204:207], v[18:21]
	v_mfma_f32_16x16x32_bf16 v[6:9], v[172:175], v[212:215], v[6:9]
	v_mfma_f32_16x16x32_bf16 v[2:5], v[180:183], v[212:215], v[2:5]
	s_setprio 0
	s_barrier
; #define PG8_STAGE(bufoff, gbase, voff) do { _Pragma("unroll") for (int _i = 0; _i < 2; ++_i) \
;         __builtin_amdgcn_global_load_lds((const unsigned*)((const char*)(gbase) + (voff)[_i]), (PG8_LAS unsigned*)(lds + (bufoff) + ldsw + _i * 8192), 16, 0, 0); } while (0)
; #define PG8_LDA(dst, b, h) do { _Pragma("unroll") for (int m = 0; m < 4; ++m) _Pragma("unroll") for (int k = 0; k < 2; ++k) dst[m][k] = *(const PG8_LAS bf16x8*)(lds + PG8_SA(b, h) + aoff + m * 2048 + k * 1024); } while (0)
; #define PG8_LDB(dst, b, h) do { _Pragma("unroll") for (int n = 0; n < 2; ++n) _Pragma("unroll") for (int k = 0; k < 2; ++k) dst[n][k] = *(const PG8_LAS bf16x8*)(lds + PG8_SB(b, h) + boff + n * 2048 + k * 1024); } while (0)
; #define PG8_MMA(ai, bj, At, Bt) do { __builtin_amdgcn_s_setprio(1); _Pragma("unroll") for (int m = 0; m < 4; ++m) _Pragma("unroll") for (int n = 0; n < 2; ++n) _Pragma("unroll") for (int k = 0; k < 2; ++k) \
;         acc[ai][bj][m][n] = __builtin_amdgcn_mfma_f32_16x16x32_bf16(Bt[n][k], At[m][k], acc[ai][bj][m][n], 0, 0, 0); __builtin_amdgcn_s_setprio(0); } while (0)
; #define PG8_WAIT_V(n) asm volatile("s_waitcnt vmcnt(" #n ")" ::: "memory")
; #define PG8_WAIT_L(n) asm volatile("s_waitcnt lgkmcnt(" #n ")" ::: "memory")
; #define PG8_BAR __builtin_amdgcn_s_barrier()
; #define PG8_SCHED __builtin_amdgcn_sched_barrier(0)
; template <class Epi, class Sched, bool ALIGN_EPI = false, bool SP2 = false, bool KSEG = false>
; __device__ __forceinline__ void gemm_phase(PG8_LAS unsigned char* lds, const Gemm g, const Sched& S, const Epi& E) {
;     ...
;             PG8_LDB(B0, 1, 0); PG8_LDB(B1, 1, 1); PG8_SCHED; PG8_LDA(At, 1, 0); PG8_STAGE(PG8_SA(0, 1), a2 + hstep, voffA);
;             PG8_WAIT_V(8); PG8_WAIT_L(0); PG8_BAR; PG8_MMA(0, 0, At, B0); PG8_MMA(0, 1, At, B1); PG8_BAR; PG8_SCHED;
	ds_read_b128 v[146:149], v250
	ds_read_b128 v[156:159], v250 offset:1024
	ds_read_b128 v[160:163], v250 offset:2048
	ds_read_b128 v[164:167], v250 offset:3072
	ds_read_b128 v[168:171], v251
	ds_read_b128 v[172:175], v251 offset:1024
	ds_read_b128 v[176:179], v251 offset:2048
	ds_read_b128 v[180:183], v251 offset:3072
	s_mov_b32 m0, s31
	v_lshl_add_u64 v[224:225], s[28:29], 0, v[140:141]
	global_load_lds_dwordx4 v[224:225], off
	s_mov_b32 m0, s36
	v_lshl_add_u64 v[224:225], s[28:29], 0, v[142:143]
	global_load_lds_dwordx4 v[224:225], off
	s_add_u32 s28, s28, 0x160000
	s_addc_u32 s29, s29, 0
	s_mov_b32 m0, s37
	v_lshl_add_u64 v[224:225], s[28:29], 0, v[140:141]
	ds_read_b128 v[184:187], v154 offset:32768
	ds_read_b128 v[188:191], v154 offset:33792
	ds_read_b128 v[192:195], v154 offset:34816
	ds_read_b128 v[196:199], v154 offset:35840
	ds_read_b128 v[200:203], v154 offset:36864
	ds_read_b128 v[204:207], v154 offset:37888
	ds_read_b128 v[208:211], v154 offset:38912
	ds_read_b128 v[212:215], v154 offset:39936
	global_load_lds_dwordx4 v[224:225], off
	s_mov_b32 m0, s38
	v_lshl_add_u64 v[224:225], s[28:29], 0, v[142:143]
	global_load_lds_dwordx4 v[224:225], off
	s_waitcnt vmcnt(8) lgkmcnt(0)
	s_barrier
	s_setprio 1
	v_mfma_f32_16x16x32_bf16 v[126:129], v[146:149], v[184:187], v[126:129]
	v_mfma_f32_16x16x32_bf16 v[122:125], v[160:163], v[184:187], v[122:125]
	v_mfma_f32_16x16x32_bf16 v[110:113], v[146:149], v[192:195], v[110:113]
	v_mfma_f32_16x16x32_bf16 v[106:109], v[160:163], v[192:195], v[106:109]
	v_mfma_f32_16x16x32_bf16 v[94:97], v[146:149], v[200:203], v[94:97]
	v_mfma_f32_16x16x32_bf16 v[90:93], v[160:163], v[200:203], v[90:93]
	v_mfma_f32_16x16x32_bf16 v[78:81], v[146:149], v[208:211], v[78:81]
	v_mfma_f32_16x16x32_bf16 v[74:77], v[160:163], v[208:211], v[74:77]
	v_mfma_f32_16x16x32_bf16 v[126:129], v[156:159], v[188:191], v[126:129]
	v_mfma_f32_16x16x32_bf16 v[122:125], v[164:167], v[188:191], v[122:125]
	v_mfma_f32_16x16x32_bf16 v[110:113], v[156:159], v[196:199], v[110:113]
	v_mfma_f32_16x16x32_bf16 v[106:109], v[164:167], v[196:199], v[106:109]
	v_mfma_f32_16x16x32_bf16 v[94:97], v[156:159], v[204:207], v[94:97]
	v_mfma_f32_16x16x32_bf16 v[90:93], v[164:167], v[204:207], v[90:93]
	v_mfma_f32_16x16x32_bf16 v[78:81], v[156:159], v[212:215], v[78:81]
	v_mfma_f32_16x16x32_bf16 v[74:77], v[164:167], v[212:215], v[74:77]
	s_setprio 0
	s_setprio 1
	v_mfma_f32_16x16x32_bf16 v[118:121], v[168:171], v[184:187], v[118:121]
	v_mfma_f32_16x16x32_bf16 v[114:117], v[176:179], v[184:187], v[114:117]
	v_mfma_f32_16x16x32_bf16 v[102:105], v[168:171], v[192:195], v[102:105]
	v_mfma_f32_16x16x32_bf16 v[98:101], v[176:179], v[192:195], v[98:101]
	v_mfma_f32_16x16x32_bf16 v[86:89], v[168:171], v[200:203], v[86:89]
	v_mfma_f32_16x16x32_bf16 v[82:85], v[176:179], v[200:203], v[82:85]
	v_mfma_f32_16x16x32_bf16 v[70:73], v[168:171], v[208:211], v[70:73]
	v_mfma_f32_16x16x32_bf16 v[66:69], v[176:179], v[208:211], v[66:69]
	v_mfma_f32_16x16x32_bf16 v[118:121], v[172:175], v[188:191], v[118:121]
	v_mfma_f32_16x16x32_bf16 v[114:117], v[180:183], v[188:191], v[114:117]
	v_mfma_f32_16x16x32_bf16 v[102:105], v[172:175], v[196:199], v[102:105]
	v_mfma_f32_16x16x32_bf16 v[98:101], v[180:183], v[196:199], v[98:101]
	v_mfma_f32_16x16x32_bf16 v[86:89], v[172:175], v[204:207], v[86:89]
	v_mfma_f32_16x16x32_bf16 v[82:85], v[180:183], v[204:207], v[82:85]
	v_mfma_f32_16x16x32_bf16 v[70:73], v[172:175], v[212:215], v[70:73]
	v_mfma_f32_16x16x32_bf16 v[66:69], v[180:183], v[212:215], v[66:69]
	s_setprio 0
	s_barrier
; #define PG8_STAGE(bufoff, gbase, voff) do { _Pragma("unroll") for (int _i = 0; _i < 2; ++_i) \
;         __builtin_amdgcn_global_load_lds((const unsigned*)((const char*)(gbase) + (voff)[_i]), (PG8_LAS unsigned*)(lds + (bufoff) + ldsw + _i * 8192), 16, 0, 0); } while (0)
; #define PG8_LDA(dst, b, h) do { _Pragma("unroll") for (int m = 0; m < 4; ++m) _Pragma("unroll") for (int k = 0; k < 2; ++k) dst[m][k] = *(const PG8_LAS bf16x8*)(lds + PG8_SA(b, h) + aoff + m * 2048 + k * 1024); } while (0)
; #define PG8_MMA(ai, bj, At, Bt) do { __builtin_amdgcn_s_setprio(1); _Pragma("unroll") for (int m = 0; m < 4; ++m) _Pragma("unroll") for (int n = 0; n < 2; ++n) _Pragma("unroll") for (int k = 0; k < 2; ++k) \
;         acc[ai][bj][m][n] = __builtin_amdgcn_mfma_f32_16x16x32_bf16(Bt[n][k], At[m][k], acc[ai][bj][m][n], 0, 0, 0); __builtin_amdgcn_s_setprio(0); } while (0)
; #define PG8_WAIT_V(n) asm volatile("s_waitcnt vmcnt(" #n ")" ::: "memory")
; #define PG8_WAIT_L(n) asm volatile("s_waitcnt lgkmcnt(" #n ")" ::: "memory")
; #define PG8_BAR __builtin_amdgcn_s_barrier()
; #define PG8_SCHED __builtin_amdgcn_sched_barrier(0)
; template <class Epi, class Sched, bool ALIGN_EPI = false, bool SP2 = false, bool KSEG = false>
; __device__ __forceinline__ void gemm_phase(PG8_LAS unsigned char* lds, const Gemm g, const Sched& S, const Epi& E) {
;     ...
;         for (int t = 0; t < nt; t += 2) {
;             const bool last = (t == nt - 2);
;             const char* a1 = cA + (size_t)(t + 1) * kstep;
;             const char* a2 = last ? nA : cA + (size_t)(t + 2) * kstep; const char* b2 = last ? nB : cB + (size_t)(t + 2) * kstep;
;             const char* a3 = a2 + kstep; const char* b3 = b2 + kstep;
;     ...
;             PG8_LDA(At, 1, 1); PG8_STAGE(PG8_SB(1, 0), b3, voffB); PG8_STAGE(PG8_SB(1, 1), b3 + hstep, voffB); PG8_STAGE(PG8_SA(1, 0), a3, voffA);
;             PG8_WAIT_V(8); PG8_WAIT_L(0); PG8_BAR; PG8_MMA(1, 0, At, B0); PG8_MMA(1, 1, At, B1); PG8_BAR; PG8_SCHED;
	v_lshl_add_u64 v[216:217], v[216:217], 0, s[12:13]
	s_add_i32 m0, s30, 0x18000
	ds_read_b128 v[184:187], v154 offset:49152
	ds_read_b128 v[188:191], v154 offset:50176
	ds_read_b128 v[192:195], v154 offset:51200
	ds_read_b128 v[196:199], v154 offset:52224
	ds_read_b128 v[200:203], v154 offset:53248
	ds_read_b128 v[204:207], v154 offset:54272
	ds_read_b128 v[208:211], v154 offset:55296
	ds_read_b128 v[212:215], v154 offset:56320
	global_load_lds_dwordx4 v[216:217], off
	s_add_i32 m0, m0, 0x2000
	s_add_u32 s26, s26, 0x160080
	v_lshl_add_u64 v[216:217], v[218:219], 0, s[12:13]
	s_addc_u32 s27, s27, 0
	global_load_lds_dwordx4 v[216:217], off
	s_add_i32 m0, s30, 0x1c000
	v_lshl_add_u64 v[216:217], s[26:27], 0, v[130:131]
	global_load_lds_dwordx4 v[216:217], off
	s_add_i32 m0, m0, 0x2000
	v_lshl_add_u64 v[216:217], s[26:27], 0, v[144:145]
	global_load_lds_dwordx4 v[216:217], off
	s_waitcnt vmcnt(6) lgkmcnt(0)
	s_barrier
	s_setprio 1
	v_mfma_f32_16x16x32_bf16 v[62:65], v[146:149], v[184:187], v[62:65]
	v_mfma_f32_16x16x32_bf16 v[58:61], v[160:163], v[184:187], v[58:61]
	v_mfma_f32_16x16x32_bf16 v[46:49], v[146:149], v[192:195], v[46:49]
	v_mfma_f32_16x16x32_bf16 v[42:45], v[160:163], v[192:195], v[42:45]
	v_mfma_f32_16x16x32_bf16 v[30:33], v[146:149], v[200:203], v[30:33]
	v_mfma_f32_16x16x32_bf16 v[26:29], v[160:163], v[200:203], v[26:29]
	v_mfma_f32_16x16x32_bf16 v[14:17], v[146:149], v[208:211], v[14:17]
	v_mfma_f32_16x16x32_bf16 v[10:13], v[160:163], v[208:211], v[10:13]
	v_mfma_f32_16x16x32_bf16 v[62:65], v[156:159], v[188:191], v[62:65]
	v_mfma_f32_16x16x32_bf16 v[58:61], v[164:167], v[188:191], v[58:61]
	v_mfma_f32_16x16x32_bf16 v[46:49], v[156:159], v[196:199], v[46:49]
	v_mfma_f32_16x16x32_bf16 v[42:45], v[164:167], v[196:199], v[42:45]
	v_mfma_f32_16x16x32_bf16 v[30:33], v[156:159], v[204:207], v[30:33]
	v_mfma_f32_16x16x32_bf16 v[26:29], v[164:167], v[204:207], v[26:29]
	v_mfma_f32_16x16x32_bf16 v[14:17], v[156:159], v[212:215], v[14:17]
	v_mfma_f32_16x16x32_bf16 v[10:13], v[164:167], v[212:215], v[10:13]
	s_setprio 0
	s_setprio 1
	v_mfma_f32_16x16x32_bf16 v[54:57], v[168:171], v[184:187], v[54:57]
	s_add_i32 s50, s50, 2
	v_mfma_f32_16x16x32_bf16 v[50:53], v[176:179], v[184:187], v[50:53]
	s_add_u32 s24, s24, 0x100
	v_mfma_f32_16x16x32_bf16 v[38:41], v[168:171], v[192:195], v[38:41]
	s_addc_u32 s25, s25, 0
	v_mfma_f32_16x16x32_bf16 v[34:37], v[176:179], v[192:195], v[34:37]
	s_add_u32 s48, s48, 0x100
	v_mfma_f32_16x16x32_bf16 v[22:25], v[168:171], v[200:203], v[22:25]
	s_addc_u32 s49, s49, 0
	v_mfma_f32_16x16x32_bf16 v[18:21], v[176:179], v[200:203], v[18:21]
	s_add_u32 s26, s24, 0xffea0080
	v_mfma_f32_16x16x32_bf16 v[6:9], v[168:171], v[208:211], v[6:9]
	s_addc_u32 s27, s25, -1
	v_mfma_f32_16x16x32_bf16 v[2:5], v[176:179], v[208:211], v[2:5]
	s_cmpk_eq_i32 s50, 0x54
	v_mfma_f32_16x16x32_bf16 v[54:57], v[172:175], v[188:191], v[54:57]
	s_cselect_b32 s29, s21, s27
	v_mfma_f32_16x16x32_bf16 v[50:53], v[180:183], v[188:191], v[50:53]
	s_cselect_b32 s28, s20, s26
	v_mfma_f32_16x16x32_bf16 v[38:41], v[172:175], v[196:199], v[38:41]
	s_cselect_b32 s27, s9, s49
	v_mfma_f32_16x16x32_bf16 v[34:37], v[180:183], v[196:199], v[34:37]
	s_cselect_b32 s26, s8, s48
	v_mfma_f32_16x16x32_bf16 v[22:25], v[172:175], v[204:207], v[22:25]
	s_add_u32 s98, s24, 0xffea0000
	v_mfma_f32_16x16x32_bf16 v[18:21], v[180:183], v[204:207], v[18:21]
	s_addc_u32 s99, s25, -1
	v_mfma_f32_16x16x32_bf16 v[6:9], v[172:175], v[212:215], v[6:9]
	s_cmpk_lt_u32 s50, 0x56
	v_mfma_f32_16x16x32_bf16 v[2:5], v[180:183], v[212:215], v[2:5]
	s_setprio 0
	s_barrier
	s_cbranch_scc1 .LBB0_621
	s_andn2_b64 vcc, exec, s[18:19]
	s_cbranch_vccnz .LBB0_624
	s_barrier
